# hazard fix: s_nop 0 restored between M0 write and LDS-DMA at 4 sites (Table 11 row 16); otherwise identical to the head-trim version
# speedup vs baseline: 1.0031x; 1.0031x over previous
; #define PG8_STAGE(bufoff, gbase, voff) do { _Pragma("unroll") for (int _i = 0; _i < 2; ++_i) \
;     __builtin_amdgcn_global_load_lds((const unsigned*)((const char*)(gbase) + (voff)[_i]), (LAS unsigned*)(lds + (bufoff) + ldsw + _i * 8192), 16, 0, 0); } while (0)
; #define PG8_LDA(dst, b, h) do { _Pragma("unroll") for (int m = 0; m < 4; ++m) _Pragma("unroll") for (int k = 0; k < 2; ++k) dst[m][k] = *(const LAS bf16x8*)(lds + PG8_SA(b, h) + aoff + m * 2048 + k * 1024); } while (0)
; #define PG8_LDB(dst, b, h) do { _Pragma("unroll") for (int n = 0; n < 2; ++n) _Pragma("unroll") for (int k = 0; k < 2; ++k) dst[n][k] = *(const LAS bf16x8*)(lds + PG8_SB(b, h) + boff + n * 2048 + k * 1024); } while (0)
; #define PG8_MMA(ai, bj, At, Bt) do { __builtin_amdgcn_s_setprio(1); _Pragma("unroll") for (int m = 0; m < 4; ++m) _Pragma("unroll") for (int n = 0; n < 2; ++n) _Pragma("unroll") for (int k = 0; k < 2; ++k) \
;     acc[ai][bj][m][n] = __builtin_amdgcn_mfma_f32_16x16x32_bf16(Bt[n][k], At[m][k], acc[ai][bj][m][n], 0, 0, 0); __builtin_amdgcn_s_setprio(0); } while (0)
; #define PG8_WAIT_V(n) asm volatile("s_waitcnt vmcnt(" #n ")" ::: "memory")
; #define PG8_BAR __builtin_amdgcn_s_barrier()
; template <class Epi>
; DI void gemm_phase(LAS unsigned char* lds, const Gemm g, const Epi& E) {
;     ...
;     const bool has_next = S.next(ui + 1, nxt);
;     const char* nA = has_next ? PG8_APTR(nxt) : cA; const char* nB = has_next ? (const char*)g.Bt + (size_t)nxt.pn * tstepB : cB;
;     for (int t = 0; t < nt; t += 2) {
;       const bool last = (t == nt - 2);
;       const char* a1 = cA + (size_t)(t + 1) * kstep;
;       const char* a2 = last ? nA : cA + (size_t)(t + 2) * kstep; const char* b2 = last ? nB : cB + (size_t)(t + 2) * kstep;
;       const char* a3 = a2 + kstep; const char* b3 = b2 + kstep;
;       PG8_LDB(B0, 0, 0); PG8_SCHED; PG8_LDA(At, 0, 0); PG8_STAGE(PG8_SA(1, 1), a1 + hstepA, voffA);
;       PG8_WAIT_L(8); PG8_BAR; PG8_WAIT_L(0); PG8_MMA(0, 0, At, B0); PG8_BAR; PG8_SCHED;
;       PG8_LDB(B1, 0, 1); PG8_STAGE(PG8_SB(0, 0), b2, voffB);
;       PG8_BAR; PG8_WAIT_L(0); PG8_MMA(0, 1, At, B1); PG8_BAR;
;       PG8_LDA(At, 0, 1); PG8_STAGE(PG8_SA(0, 0), a2, voffA);
;       PG8_BAR; PG8_WAIT_L(0); PG8_MMA(1, 0, At, B0); PG8_BAR; PG8_SCHED;
;       PG8_STAGE(PG8_SB(0, 1), b2 + hstepB, voffB);
;       PG8_WAIT_V(6); PG8_BAR; PG8_MMA(1, 1, At, B1); PG8_BAR;
.LBB0_189:
	s_ashr_i32 s13, s12, 31
	v_cmp_lt_i64_e32 vcc, s[18:19], v[170:171]
	s_lshl_b64 s[18:19], s[12:13], 20
	s_add_u32 s18, s42, s18
	s_addc_u32 s19, s43, s19
	s_and_b64 s[22:23], vcc, exec
	s_cselect_b32 s13, s19, s31
	s_cselect_b32 s55, s18, s30
	s_ashr_i32 s3, s2, 31
	s_lshl_b64 s[22:23], s[2:3], 20
	s_add_u32 s22, s44, s22
	s_addc_u32 s23, s45, s23
	s_and_b64 s[40:41], vcc, exec
	s_cselect_b32 s3, s23, s37
	s_cselect_b32 s56, s22, s36
	s_add_u32 s30, s30, 0x80080
	s_addc_u32 s31, s31, 0
	s_add_u32 s57, s36, 0x100
	s_addc_u32 s58, s37, 0
	s_mov_b32 s59, -2
	v_add_u32_e32 v248, 0x10000, v143
	ds_read_b128 v[146:149], v248
	ds_read_b128 v[150:153], v248 offset:1024
	ds_read_b128 v[154:157], v248 offset:2048
	ds_read_b128 v[158:161], v248 offset:3072
	s_add_i32 m0, s27, 0xc000
	ds_read_b128 v[180:183], v145
	ds_read_b128 v[184:187], v145 offset:1024
	ds_read_b128 v[188:191], v145 offset:2048
	ds_read_b128 v[192:195], v145 offset:3072
	ds_read_b128 v[196:199], v145 offset:4096
	ds_read_b128 v[200:203], v145 offset:5120
	ds_read_b128 v[208:211], v145 offset:6144
	ds_read_b128 v[212:215], v145 offset:7168
	global_load_lds_dwordx4 v138, s[30:31]
	s_add_i32 m0, s27, 0xe000
	s_nop 0
	global_load_lds_dwordx4 v140, s[30:31]
	s_waitcnt lgkmcnt(8)
	s_barrier
	s_setprio 1
	s_waitcnt lgkmcnt(0)
	v_mfma_f32_16x16x32_bf16 v[128:131], v[146:149], v[180:183], 0
	s_add_u32 s36, s30, 0xfff80080
	s_addc_u32 s37, s31, -1
	v_mfma_f32_16x16x32_bf16 v[120:123], v[154:157], v[180:183], 0
	s_add_i32 s60, 0, 0x10000
	v_mfma_f32_16x16x32_bf16 v[112:115], v[146:149], v[188:191], 0
	s_cmp_eq_u32 s59, 28
	s_cselect_b32 s41, s13, s37
	s_cselect_b32 s40, s55, s36
	s_cselect_b32 s37, s3, s58
	s_cselect_b32 s36, s56, s57
	v_mfma_f32_16x16x32_bf16 v[104:107], v[154:157], v[188:191], 0
	v_mfma_f32_16x16x32_bf16 v[96:99], v[146:149], v[196:199], 0
	v_mfma_f32_16x16x32_bf16 v[88:91], v[154:157], v[196:199], 0
	v_mfma_f32_16x16x32_bf16 v[80:83], v[146:149], v[208:211], 0
	v_mfma_f32_16x16x32_bf16 v[72:75], v[154:157], v[208:211], 0
	v_mfma_f32_16x16x32_bf16 v[128:131], v[150:153], v[184:187], v[128:131]
	v_mfma_f32_16x16x32_bf16 v[120:123], v[158:161], v[184:187], v[120:123]
	v_mfma_f32_16x16x32_bf16 v[112:115], v[150:153], v[192:195], v[112:115]
	v_mfma_f32_16x16x32_bf16 v[104:107], v[158:161], v[192:195], v[104:107]
	v_mfma_f32_16x16x32_bf16 v[96:99], v[150:153], v[200:203], v[96:99]
	v_mfma_f32_16x16x32_bf16 v[88:91], v[158:161], v[200:203], v[88:91]
	s_setprio 2
	s_barrier
	v_mfma_f32_16x16x32_bf16 v[80:83], v[150:153], v[212:215], v[80:83]
	v_mfma_f32_16x16x32_bf16 v[72:75], v[158:161], v[212:215], v[72:75]
	s_setprio 0
	s_add_i32 s62, 0, 0x14000
	s_add_i32 s60, s60, s47
	ds_read_b128 v[216:219], v248 offset:16384
	ds_read_b128 v[220:223], v248 offset:17408
	ds_read_b128 v[224:227], v248 offset:18432
	ds_read_b128 v[228:231], v248 offset:19456
	s_add_u32 s98, s36, 0x80
	s_addc_u32 s99, s37, 0
	s_mov_b32 m0, s60
	s_nop 0
	global_load_lds_dwordx4 v2, s[36:37]
	s_add_i32 m0, s60, 0x2000
	s_nop 0
	global_load_lds_dwordx4 v132, s[36:37]
	s_barrier
	s_setprio 1
	s_waitcnt lgkmcnt(0)
	v_mfma_f32_16x16x32_bf16 v[124:127], v[216:219], v[180:183], 0
	v_mfma_f32_16x16x32_bf16 v[116:119], v[224:227], v[180:183], 0
	v_mfma_f32_16x16x32_bf16 v[108:111], v[216:219], v[188:191], 0
	v_mfma_f32_16x16x32_bf16 v[100:103], v[224:227], v[188:191], 0
	v_mfma_f32_16x16x32_bf16 v[92:95], v[216:219], v[196:199], 0
	v_mfma_f32_16x16x32_bf16 v[84:87], v[224:227], v[196:199], 0
	v_mfma_f32_16x16x32_bf16 v[76:79], v[216:219], v[208:211], 0
	v_mfma_f32_16x16x32_bf16 v[68:71], v[224:227], v[208:211], 0
	v_mfma_f32_16x16x32_bf16 v[124:127], v[220:223], v[184:187], v[124:127]
	v_mfma_f32_16x16x32_bf16 v[116:119], v[228:231], v[184:187], v[116:119]
	v_mfma_f32_16x16x32_bf16 v[108:111], v[220:223], v[192:195], v[108:111]
	v_mfma_f32_16x16x32_bf16 v[100:103], v[228:231], v[192:195], v[100:103]
	v_mfma_f32_16x16x32_bf16 v[92:95], v[220:223], v[200:203], v[92:95]
	v_mfma_f32_16x16x32_bf16 v[84:87], v[228:231], v[200:203], v[84:87]
	s_setprio 2
	s_barrier
	v_mfma_f32_16x16x32_bf16 v[76:79], v[220:223], v[212:215], v[76:79]
	v_mfma_f32_16x16x32_bf16 v[68:71], v[228:231], v[212:215], v[68:71]
	s_setprio 0
	s_mov_b32 m0, s27
	s_add_u32 s100, s40, 0x80
	s_addc_u32 s101, s41, 0
	ds_read_b128 v[180:183], v145 offset:16384
	ds_read_b128 v[184:187], v145 offset:17408
	ds_read_b128 v[188:191], v145 offset:18432
	ds_read_b128 v[192:195], v145 offset:19456
	ds_read_b128 v[196:199], v145 offset:20480
	ds_read_b128 v[200:203], v145 offset:21504
	ds_read_b128 v[208:211], v145 offset:22528
	ds_read_b128 v[212:215], v145 offset:23552
	global_load_lds_dwordx4 v136, s[40:41]
	s_mov_b32 m0, s48
	s_nop 0
	global_load_lds_dwordx4 v134, s[40:41]
	s_waitcnt vmcnt(10)
	s_barrier
	s_setprio 1
	s_waitcnt lgkmcnt(0)
	v_mfma_f32_16x16x32_bf16 v[64:67], v[146:149], v[180:183], 0
	v_mfma_f32_16x16x32_bf16 v[56:59], v[154:157], v[180:183], 0
	v_mfma_f32_16x16x32_bf16 v[48:51], v[146:149], v[188:191], 0
	v_mfma_f32_16x16x32_bf16 v[40:43], v[154:157], v[188:191], 0
	v_mfma_f32_16x16x32_bf16 v[32:35], v[146:149], v[196:199], 0
	v_mfma_f32_16x16x32_bf16 v[24:27], v[154:157], v[196:199], 0
	v_mfma_f32_16x16x32_bf16 v[16:19], v[146:149], v[208:211], 0
	v_mfma_f32_16x16x32_bf16 v[8:11], v[154:157], v[208:211], 0
	v_mfma_f32_16x16x32_bf16 v[64:67], v[150:153], v[184:187], v[64:67]
	v_mfma_f32_16x16x32_bf16 v[56:59], v[158:161], v[184:187], v[56:59]
	v_mfma_f32_16x16x32_bf16 v[48:51], v[150:153], v[192:195], v[48:51]
	v_mfma_f32_16x16x32_bf16 v[40:43], v[158:161], v[192:195], v[40:43]
	v_mfma_f32_16x16x32_bf16 v[32:35], v[150:153], v[200:203], v[32:35]
	v_mfma_f32_16x16x32_bf16 v[24:27], v[158:161], v[200:203], v[24:27]
	s_setprio 2
	s_barrier
; #define PG8_STAGE(bufoff, gbase, voff) do { _Pragma("unroll") for (int _i = 0; _i < 2; ++_i) \
;     __builtin_amdgcn_global_load_lds((const unsigned*)((const char*)(gbase) + (voff)[_i]), (LAS unsigned*)(lds + (bufoff) + ldsw + _i * 8192), 16, 0, 0); } while (0)
; #define PG8_LDA(dst, b, h) do { _Pragma("unroll") for (int m = 0; m < 4; ++m) _Pragma("unroll") for (int k = 0; k < 2; ++k) dst[m][k] = *(const LAS bf16x8*)(lds + PG8_SA(b, h) + aoff + m * 2048 + k * 1024); } while (0)
; #define PG8_LDB(dst, b, h) do { _Pragma("unroll") for (int n = 0; n < 2; ++n) _Pragma("unroll") for (int k = 0; k < 2; ++k) dst[n][k] = *(const LAS bf16x8*)(lds + PG8_SB(b, h) + boff + n * 2048 + k * 1024); } while (0)
; #define PG8_MMA(ai, bj, At, Bt) do { __builtin_amdgcn_s_setprio(1); _Pragma("unroll") for (int m = 0; m < 4; ++m) _Pragma("unroll") for (int n = 0; n < 2; ++n) _Pragma("unroll") for (int k = 0; k < 2; ++k) \
;     acc[ai][bj][m][n] = __builtin_amdgcn_mfma_f32_16x16x32_bf16(Bt[n][k], At[m][k], acc[ai][bj][m][n], 0, 0, 0); __builtin_amdgcn_s_setprio(0); } while (0)
; #define PG8_WAIT_V(n) asm volatile("s_waitcnt vmcnt(" #n ")" ::: "memory")
; #define PG8_WAIT_L(n) asm volatile("s_waitcnt lgkmcnt(" #n ")" ::: "memory")
; #define PG8_BAR __builtin_amdgcn_s_barrier()
; #define PG8_SCHED __builtin_amdgcn_sched_barrier(0)
; template <class Epi>
; DI void gemm_phase(LAS unsigned char* lds, const Gemm g, const Epi& E) {
;     ...
;       PG8_WAIT_V(6); PG8_BAR; PG8_MMA(1, 1, At, B1); PG8_BAR;
;       PG8_LDB(B0, 1, 0); PG8_SCHED; PG8_LDA(At, 1, 0); PG8_STAGE(PG8_SA(0, 1), a2 + hstepA, voffA);
;       PG8_WAIT_L(8); PG8_BAR; PG8_WAIT_L(0); PG8_MMA(0, 0, At, B0); PG8_BAR; PG8_SCHED;
;       PG8_LDB(B1, 1, 1); PG8_STAGE(PG8_SB(1, 0), b3, voffB);
;       PG8_BAR; PG8_WAIT_L(0); PG8_MMA(0, 1, At, B1); PG8_BAR;
;       PG8_LDA(At, 1, 1); PG8_STAGE(PG8_SA(1, 0), a3, voffA);
;       PG8_BAR; PG8_WAIT_L(0); PG8_MMA(1, 0, At, B0); PG8_BAR; PG8_SCHED;
	v_mfma_f32_16x16x32_bf16 v[16:19], v[150:153], v[212:215], v[16:19]
	v_mfma_f32_16x16x32_bf16 v[8:11], v[158:161], v[212:215], v[8:11]
	s_setprio 0
	ds_read_b128 v[146:149], v248 offset:32768
	ds_read_b128 v[150:153], v248 offset:33792
	ds_read_b128 v[154:157], v248 offset:34816
	ds_read_b128 v[158:161], v248 offset:35840
	s_add_u32 s60, s36, 0x80000
	s_addc_u32 s61, s37, 0
	s_add_i32 s62, s62, s47
	s_mov_b32 m0, s62
	s_nop 0
	global_load_lds_dwordx4 v2, s[60:61]
	s_add_i32 m0, s62, 0x2000
	s_nop 0
	global_load_lds_dwordx4 v132, s[60:61]
	s_waitcnt vmcnt(6)
	s_barrier
	s_setprio 1
	v_mfma_f32_16x16x32_bf16 v[60:63], v[216:219], v[180:183], 0
	v_mfma_f32_16x16x32_bf16 v[52:55], v[224:227], v[180:183], 0
	v_mfma_f32_16x16x32_bf16 v[44:47], v[216:219], v[188:191], 0
	v_mfma_f32_16x16x32_bf16 v[36:39], v[224:227], v[188:191], 0
	v_mfma_f32_16x16x32_bf16 v[28:31], v[216:219], v[196:199], 0
	v_mfma_f32_16x16x32_bf16 v[20:23], v[224:227], v[196:199], 0
	v_mfma_f32_16x16x32_bf16 v[12:15], v[216:219], v[208:211], 0
	v_mfma_f32_16x16x32_bf16 v[4:7], v[224:227], v[208:211], 0
	v_mfma_f32_16x16x32_bf16 v[60:63], v[220:223], v[184:187], v[60:63]
	v_mfma_f32_16x16x32_bf16 v[52:55], v[228:231], v[184:187], v[52:55]
	v_mfma_f32_16x16x32_bf16 v[44:47], v[220:223], v[192:195], v[44:47]
	v_mfma_f32_16x16x32_bf16 v[36:39], v[228:231], v[192:195], v[36:39]
	v_mfma_f32_16x16x32_bf16 v[28:31], v[220:223], v[200:203], v[28:31]
	v_mfma_f32_16x16x32_bf16 v[20:23], v[228:231], v[200:203], v[20:23]
	s_setprio 2
	s_barrier
	v_mfma_f32_16x16x32_bf16 v[12:15], v[220:223], v[212:215], v[12:15]
	v_mfma_f32_16x16x32_bf16 v[4:7], v[228:231], v[212:215], v[4:7]
	s_setprio 0
	s_add_i32 s60, 0, 0x18000
	s_add_u32 s40, s40, 0x80000
	s_addc_u32 s41, s41, 0
	s_mov_b32 m0, s49
	ds_read_b128 v[180:183], v145 offset:32768
	ds_read_b128 v[184:187], v145 offset:33792
	ds_read_b128 v[188:191], v145 offset:34816
	ds_read_b128 v[192:195], v145 offset:35840
	ds_read_b128 v[196:199], v145 offset:36864
	ds_read_b128 v[200:203], v145 offset:37888
	ds_read_b128 v[208:211], v145 offset:38912
	ds_read_b128 v[212:215], v145 offset:39936
	global_load_lds_dwordx4 v136, s[40:41]
	s_mov_b32 m0, s50
	s_nop 0
	global_load_lds_dwordx4 v134, s[40:41]
	s_waitcnt lgkmcnt(8)
	s_barrier
	s_setprio 1
	s_waitcnt lgkmcnt(0)
	v_mfma_f32_16x16x32_bf16 v[128:131], v[146:149], v[180:183], v[128:131]
	v_mfma_f32_16x16x32_bf16 v[120:123], v[154:157], v[180:183], v[120:123]
	v_mfma_f32_16x16x32_bf16 v[112:115], v[146:149], v[188:191], v[112:115]
	v_mfma_f32_16x16x32_bf16 v[104:107], v[154:157], v[188:191], v[104:107]
	v_mfma_f32_16x16x32_bf16 v[96:99], v[146:149], v[196:199], v[96:99]
	v_mfma_f32_16x16x32_bf16 v[88:91], v[154:157], v[196:199], v[88:91]
	v_mfma_f32_16x16x32_bf16 v[80:83], v[146:149], v[208:211], v[80:83]
	v_mfma_f32_16x16x32_bf16 v[72:75], v[154:157], v[208:211], v[72:75]
	v_mfma_f32_16x16x32_bf16 v[128:131], v[150:153], v[184:187], v[128:131]
	v_mfma_f32_16x16x32_bf16 v[120:123], v[158:161], v[184:187], v[120:123]
	v_mfma_f32_16x16x32_bf16 v[112:115], v[150:153], v[192:195], v[112:115]
	v_mfma_f32_16x16x32_bf16 v[104:107], v[158:161], v[192:195], v[104:107]
	v_mfma_f32_16x16x32_bf16 v[96:99], v[150:153], v[200:203], v[96:99]
	v_mfma_f32_16x16x32_bf16 v[88:91], v[158:161], v[200:203], v[88:91]
	s_setprio 2
	s_barrier
	v_mfma_f32_16x16x32_bf16 v[80:83], v[150:153], v[212:215], v[80:83]
	v_mfma_f32_16x16x32_bf16 v[72:75], v[158:161], v[212:215], v[72:75]
	s_setprio 0
	s_add_i32 s40, 0, 0x1c000
	s_add_i32 s41, s60, s47
	s_mov_b32 m0, s41
	ds_read_b128 v[216:219], v248 offset:49152
	ds_read_b128 v[220:223], v248 offset:50176
	ds_read_b128 v[224:227], v248 offset:51200
	ds_read_b128 v[228:231], v248 offset:52224
	global_load_lds_dwordx4 v2, s[98:99]
	s_add_i32 m0, s41, 0x2000
	s_nop 0
	global_load_lds_dwordx4 v132, s[98:99]
	s_barrier
	s_setprio 1
	s_waitcnt lgkmcnt(0)
	v_mfma_f32_16x16x32_bf16 v[124:127], v[216:219], v[180:183], v[124:127]
	v_mfma_f32_16x16x32_bf16 v[116:119], v[224:227], v[180:183], v[116:119]
	v_mfma_f32_16x16x32_bf16 v[108:111], v[216:219], v[188:191], v[108:111]
	v_mfma_f32_16x16x32_bf16 v[100:103], v[224:227], v[188:191], v[100:103]
	v_mfma_f32_16x16x32_bf16 v[92:95], v[216:219], v[196:199], v[92:95]
	v_mfma_f32_16x16x32_bf16 v[84:87], v[224:227], v[196:199], v[84:87]
	v_mfma_f32_16x16x32_bf16 v[76:79], v[216:219], v[208:211], v[76:79]
	v_mfma_f32_16x16x32_bf16 v[68:71], v[224:227], v[208:211], v[68:71]
	v_mfma_f32_16x16x32_bf16 v[124:127], v[220:223], v[184:187], v[124:127]
	v_mfma_f32_16x16x32_bf16 v[116:119], v[228:231], v[184:187], v[116:119]
	v_mfma_f32_16x16x32_bf16 v[108:111], v[220:223], v[192:195], v[108:111]
	v_mfma_f32_16x16x32_bf16 v[100:103], v[228:231], v[192:195], v[100:103]
	v_mfma_f32_16x16x32_bf16 v[92:95], v[220:223], v[200:203], v[92:95]
	v_mfma_f32_16x16x32_bf16 v[84:87], v[228:231], v[200:203], v[84:87]
	s_setprio 2
	s_barrier
	v_mfma_f32_16x16x32_bf16 v[76:79], v[220:223], v[212:215], v[76:79]
	v_mfma_f32_16x16x32_bf16 v[68:71], v[228:231], v[212:215], v[68:71]
	s_setprio 0
	s_mov_b32 m0, s51
	ds_read_b128 v[180:183], v145 offset:49152
	ds_read_b128 v[184:187], v145 offset:50176
	ds_read_b128 v[188:191], v145 offset:51200
	ds_read_b128 v[192:195], v145 offset:52224
	ds_read_b128 v[196:199], v145 offset:53248
	ds_read_b128 v[200:203], v145 offset:54272
	ds_read_b128 v[208:211], v145 offset:55296
	ds_read_b128 v[212:215], v145 offset:56320
	global_load_lds_dwordx4 v136, s[100:101]
	s_mov_b32 m0, s52
	s_nop 0
	global_load_lds_dwordx4 v134, s[100:101]
	s_waitcnt vmcnt(10)
	s_barrier
; #define PG8_STAGE(bufoff, gbase, voff) do { _Pragma("unroll") for (int _i = 0; _i < 2; ++_i) \
;     __builtin_amdgcn_global_load_lds((const unsigned*)((const char*)(gbase) + (voff)[_i]), (LAS unsigned*)(lds + (bufoff) + ldsw + _i * 8192), 16, 0, 0); } while (0)
; #define PG8_LDA(dst, b, h) do { _Pragma("unroll") for (int m = 0; m < 4; ++m) _Pragma("unroll") for (int k = 0; k < 2; ++k) dst[m][k] = *(const LAS bf16x8*)(lds + PG8_SA(b, h) + aoff + m * 2048 + k * 1024); } while (0)
; #define PG8_LDB(dst, b, h) do { _Pragma("unroll") for (int n = 0; n < 2; ++n) _Pragma("unroll") for (int k = 0; k < 2; ++k) dst[n][k] = *(const LAS bf16x8*)(lds + PG8_SB(b, h) + boff + n * 2048 + k * 1024); } while (0)
; #define PG8_MMA(ai, bj, At, Bt) do { __builtin_amdgcn_s_setprio(1); _Pragma("unroll") for (int m = 0; m < 4; ++m) _Pragma("unroll") for (int n = 0; n < 2; ++n) _Pragma("unroll") for (int k = 0; k < 2; ++k) \
;     acc[ai][bj][m][n] = __builtin_amdgcn_mfma_f32_16x16x32_bf16(Bt[n][k], At[m][k], acc[ai][bj][m][n], 0, 0, 0); __builtin_amdgcn_s_setprio(0); } while (0)
; #define PG8_WAIT_V(n) asm volatile("s_waitcnt vmcnt(" #n ")" ::: "memory")
; #define PG8_WAIT_L(n) asm volatile("s_waitcnt lgkmcnt(" #n ")" ::: "memory")
; #define PG8_BAR __builtin_amdgcn_s_barrier()
; #define PG8_SCHED __builtin_amdgcn_sched_barrier(0)
; template <class Epi>
; DI void gemm_phase(LAS unsigned char* lds, const Gemm g, const Epi& E) {
;     ...
;       PG8_LDB(B0, 0, 0); PG8_SCHED; PG8_LDA(At, 0, 0); PG8_STAGE(PG8_SA(1, 1), a1 + hstepA, voffA);
;       PG8_WAIT_L(8); PG8_BAR; PG8_WAIT_L(0); PG8_MMA(0, 0, At, B0); PG8_BAR; PG8_SCHED;
;       PG8_LDB(B1, 0, 1); PG8_STAGE(PG8_SB(0, 0), b2, voffB);
;       PG8_BAR; PG8_WAIT_L(0); PG8_MMA(0, 1, At, B1); PG8_BAR;
;       PG8_LDA(At, 0, 1); PG8_STAGE(PG8_SA(0, 0), a2, voffA);
;     ...
;       PG8_BAR; PG8_WAIT_L(0); PG8_MMA(1, 0, At, B0); PG8_BAR; PG8_SCHED;
;       PG8_STAGE(PG8_SB(1, 1), b3 + hstepB, voffB);
;       PG8_WAIT_V(6); PG8_BAR; PG8_MMA(1, 1, At, B1); PG8_BAR;
	s_setprio 1
	s_waitcnt lgkmcnt(0)
	v_mfma_f32_16x16x32_bf16 v[64:67], v[146:149], v[180:183], v[64:67]
	v_mfma_f32_16x16x32_bf16 v[56:59], v[154:157], v[180:183], v[56:59]
	v_mfma_f32_16x16x32_bf16 v[48:51], v[146:149], v[188:191], v[48:51]
	v_mfma_f32_16x16x32_bf16 v[40:43], v[154:157], v[188:191], v[40:43]
	v_mfma_f32_16x16x32_bf16 v[32:35], v[146:149], v[196:199], v[32:35]
	v_mfma_f32_16x16x32_bf16 v[24:27], v[154:157], v[196:199], v[24:27]
	v_mfma_f32_16x16x32_bf16 v[16:19], v[146:149], v[208:211], v[16:19]
	v_mfma_f32_16x16x32_bf16 v[8:11], v[154:157], v[208:211], v[8:11]
	v_mfma_f32_16x16x32_bf16 v[64:67], v[150:153], v[184:187], v[64:67]
	v_mfma_f32_16x16x32_bf16 v[56:59], v[158:161], v[184:187], v[56:59]
	v_mfma_f32_16x16x32_bf16 v[48:51], v[150:153], v[192:195], v[48:51]
	v_mfma_f32_16x16x32_bf16 v[40:43], v[158:161], v[192:195], v[40:43]
	v_mfma_f32_16x16x32_bf16 v[32:35], v[150:153], v[200:203], v[32:35]
	v_mfma_f32_16x16x32_bf16 v[24:27], v[158:161], v[200:203], v[24:27]
	s_setprio 2
	s_barrier
	v_mfma_f32_16x16x32_bf16 v[16:19], v[150:153], v[212:215], v[16:19]
	v_mfma_f32_16x16x32_bf16 v[8:11], v[158:161], v[212:215], v[8:11]
	s_setprio 0
	ds_read_b128 v[146:149], v248
	ds_read_b128 v[150:153], v248 offset:1024
	ds_read_b128 v[154:157], v248 offset:2048
	ds_read_b128 v[158:161], v248 offset:3072
	s_add_u32 s36, s36, 0x80080
	s_addc_u32 s37, s37, 0
	s_add_i32 s40, s40, s47
	s_mov_b32 m0, s40
	s_nop 0
	global_load_lds_dwordx4 v2, s[36:37]
	s_add_i32 m0, s40, 0x2000
	s_nop 0
	global_load_lds_dwordx4 v132, s[36:37]
	s_waitcnt vmcnt(6)
	s_barrier
	s_setprio 1
	v_mfma_f32_16x16x32_bf16 v[60:63], v[216:219], v[180:183], v[60:63]
	v_mfma_f32_16x16x32_bf16 v[52:55], v[224:227], v[180:183], v[52:55]
	v_mfma_f32_16x16x32_bf16 v[44:47], v[216:219], v[188:191], v[44:47]
	v_mfma_f32_16x16x32_bf16 v[36:39], v[224:227], v[188:191], v[36:39]
	v_mfma_f32_16x16x32_bf16 v[28:31], v[216:219], v[196:199], v[28:31]
	v_mfma_f32_16x16x32_bf16 v[20:23], v[224:227], v[196:199], v[20:23]
	v_mfma_f32_16x16x32_bf16 v[12:15], v[216:219], v[208:211], v[12:15]
	v_mfma_f32_16x16x32_bf16 v[4:7], v[224:227], v[208:211], v[4:7]
	v_mfma_f32_16x16x32_bf16 v[60:63], v[220:223], v[184:187], v[60:63]
	v_mfma_f32_16x16x32_bf16 v[52:55], v[228:231], v[184:187], v[52:55]
	v_mfma_f32_16x16x32_bf16 v[44:47], v[220:223], v[192:195], v[44:47]
	v_mfma_f32_16x16x32_bf16 v[36:39], v[228:231], v[192:195], v[36:39]
	v_mfma_f32_16x16x32_bf16 v[28:31], v[220:223], v[200:203], v[28:31]
	v_mfma_f32_16x16x32_bf16 v[20:23], v[228:231], v[200:203], v[20:23]
	s_setprio 2
	s_barrier
	v_mfma_f32_16x16x32_bf16 v[12:15], v[220:223], v[212:215], v[12:15]
	v_mfma_f32_16x16x32_bf16 v[4:7], v[228:231], v[212:215], v[4:7]
	s_setprio 0
	s_add_i32 s59, s59, 2
	s_add_u32 s30, s30, 0x100
	s_addc_u32 s31, s31, 0
	s_add_u32 s57, s57, 0x100
	s_addc_u32 s58, s58, 0
	s_cmp_gt_u32 s59, 29
	s_cbranch_scc1 .Lpeel_exit_190
.LBB0_190:
	s_add_i32 m0, s27, 0xc000
	ds_read_b128 v[180:183], v145
	ds_read_b128 v[184:187], v145 offset:1024
	ds_read_b128 v[188:191], v145 offset:2048
	ds_read_b128 v[192:195], v145 offset:3072
	ds_read_b128 v[196:199], v145 offset:4096
	ds_read_b128 v[200:203], v145 offset:5120
	ds_read_b128 v[208:211], v145 offset:6144
	ds_read_b128 v[212:215], v145 offset:7168
	global_load_lds_dwordx4 v138, s[30:31]
	s_add_i32 m0, s27, 0xe000
	s_nop 0
	global_load_lds_dwordx4 v140, s[30:31]
	s_waitcnt lgkmcnt(8)
	s_barrier
	s_setprio 1
	s_waitcnt lgkmcnt(0)
	v_mfma_f32_16x16x32_bf16 v[128:131], v[146:149], v[180:183], v[128:131]
	s_add_u32 s36, s30, 0xfff80080
	s_addc_u32 s37, s31, -1
	v_mfma_f32_16x16x32_bf16 v[120:123], v[154:157], v[180:183], v[120:123]
	s_add_i32 s60, 0, 0x10000
	v_mfma_f32_16x16x32_bf16 v[112:115], v[146:149], v[188:191], v[112:115]
	s_cmp_eq_u32 s59, 28
	s_cselect_b32 s41, s13, s37
	s_cselect_b32 s40, s55, s36
	s_cselect_b32 s37, s3, s58
	s_cselect_b32 s36, s56, s57
	v_mfma_f32_16x16x32_bf16 v[104:107], v[154:157], v[188:191], v[104:107]
	v_mfma_f32_16x16x32_bf16 v[96:99], v[146:149], v[196:199], v[96:99]
	v_mfma_f32_16x16x32_bf16 v[88:91], v[154:157], v[196:199], v[88:91]
	v_mfma_f32_16x16x32_bf16 v[80:83], v[146:149], v[208:211], v[80:83]
	v_mfma_f32_16x16x32_bf16 v[72:75], v[154:157], v[208:211], v[72:75]
	v_mfma_f32_16x16x32_bf16 v[128:131], v[150:153], v[184:187], v[128:131]
	v_mfma_f32_16x16x32_bf16 v[120:123], v[158:161], v[184:187], v[120:123]
	v_mfma_f32_16x16x32_bf16 v[112:115], v[150:153], v[192:195], v[112:115]
	v_mfma_f32_16x16x32_bf16 v[104:107], v[158:161], v[192:195], v[104:107]
	v_mfma_f32_16x16x32_bf16 v[96:99], v[150:153], v[200:203], v[96:99]
	v_mfma_f32_16x16x32_bf16 v[88:91], v[158:161], v[200:203], v[88:91]
	s_setprio 2
	s_barrier
	v_mfma_f32_16x16x32_bf16 v[80:83], v[150:153], v[212:215], v[80:83]
	v_mfma_f32_16x16x32_bf16 v[72:75], v[158:161], v[212:215], v[72:75]
	s_setprio 0
	s_add_i32 s62, 0, 0x14000
	s_add_i32 s60, s60, s47
	ds_read_b128 v[216:219], v248 offset:16384
	ds_read_b128 v[220:223], v248 offset:17408
	ds_read_b128 v[224:227], v248 offset:18432
	ds_read_b128 v[228:231], v248 offset:19456
	s_add_u32 s98, s36, 0x80
	s_addc_u32 s99, s37, 0
	s_mov_b32 m0, s60
	s_nop 0
	global_load_lds_dwordx4 v2, s[36:37]
	s_add_i32 m0, s60, 0x2000
	s_nop 0
	global_load_lds_dwordx4 v132, s[36:37]
	s_barrier
; #define PG8_STAGE(bufoff, gbase, voff) do { _Pragma("unroll") for (int _i = 0; _i < 2; ++_i) \
;     __builtin_amdgcn_global_load_lds((const unsigned*)((const char*)(gbase) + (voff)[_i]), (LAS unsigned*)(lds + (bufoff) + ldsw + _i * 8192), 16, 0, 0); } while (0)
; #define PG8_LDA(dst, b, h) do { _Pragma("unroll") for (int m = 0; m < 4; ++m) _Pragma("unroll") for (int k = 0; k < 2; ++k) dst[m][k] = *(const LAS bf16x8*)(lds + PG8_SA(b, h) + aoff + m * 2048 + k * 1024); } while (0)
; #define PG8_LDB(dst, b, h) do { _Pragma("unroll") for (int n = 0; n < 2; ++n) _Pragma("unroll") for (int k = 0; k < 2; ++k) dst[n][k] = *(const LAS bf16x8*)(lds + PG8_SB(b, h) + boff + n * 2048 + k * 1024); } while (0)
; #define PG8_MMA(ai, bj, At, Bt) do { __builtin_amdgcn_s_setprio(1); _Pragma("unroll") for (int m = 0; m < 4; ++m) _Pragma("unroll") for (int n = 0; n < 2; ++n) _Pragma("unroll") for (int k = 0; k < 2; ++k) \
;     acc[ai][bj][m][n] = __builtin_amdgcn_mfma_f32_16x16x32_bf16(Bt[n][k], At[m][k], acc[ai][bj][m][n], 0, 0, 0); __builtin_amdgcn_s_setprio(0); } while (0)
; #define PG8_WAIT_V(n) asm volatile("s_waitcnt vmcnt(" #n ")" ::: "memory")
; #define PG8_WAIT_L(n) asm volatile("s_waitcnt lgkmcnt(" #n ")" ::: "memory")
; #define PG8_BAR __builtin_amdgcn_s_barrier()
; #define PG8_SCHED __builtin_amdgcn_sched_barrier(0)
; template <class Epi>
; DI void gemm_phase(LAS unsigned char* lds, const Gemm g, const Epi& E) {
;     ...
;       PG8_BAR; PG8_WAIT_L(0); PG8_MMA(0, 1, At, B1); PG8_BAR;
;       PG8_LDA(At, 0, 1); PG8_STAGE(PG8_SA(0, 0), a2, voffA);
;       PG8_BAR; PG8_WAIT_L(0); PG8_MMA(1, 0, At, B0); PG8_BAR; PG8_SCHED;
;       PG8_STAGE(PG8_SB(0, 1), b2 + hstepB, voffB);
;       PG8_WAIT_V(6); PG8_BAR; PG8_MMA(1, 1, At, B1); PG8_BAR;
;       PG8_LDB(B0, 1, 0); PG8_SCHED; PG8_LDA(At, 1, 0); PG8_STAGE(PG8_SA(0, 1), a2 + hstepA, voffA);
;       PG8_WAIT_L(8); PG8_BAR; PG8_WAIT_L(0); PG8_MMA(0, 0, At, B0); PG8_BAR; PG8_SCHED;
;       PG8_LDB(B1, 1, 1); PG8_STAGE(PG8_SB(1, 0), b3, voffB);
;       PG8_BAR; PG8_WAIT_L(0); PG8_MMA(0, 1, At, B1); PG8_BAR;
	s_setprio 1
	s_waitcnt lgkmcnt(0)
	v_mfma_f32_16x16x32_bf16 v[124:127], v[216:219], v[180:183], v[124:127]
	v_mfma_f32_16x16x32_bf16 v[116:119], v[224:227], v[180:183], v[116:119]
	v_mfma_f32_16x16x32_bf16 v[108:111], v[216:219], v[188:191], v[108:111]
	v_mfma_f32_16x16x32_bf16 v[100:103], v[224:227], v[188:191], v[100:103]
	v_mfma_f32_16x16x32_bf16 v[92:95], v[216:219], v[196:199], v[92:95]
	v_mfma_f32_16x16x32_bf16 v[84:87], v[224:227], v[196:199], v[84:87]
	v_mfma_f32_16x16x32_bf16 v[76:79], v[216:219], v[208:211], v[76:79]
	v_mfma_f32_16x16x32_bf16 v[68:71], v[224:227], v[208:211], v[68:71]
	v_mfma_f32_16x16x32_bf16 v[124:127], v[220:223], v[184:187], v[124:127]
	v_mfma_f32_16x16x32_bf16 v[116:119], v[228:231], v[184:187], v[116:119]
	v_mfma_f32_16x16x32_bf16 v[108:111], v[220:223], v[192:195], v[108:111]
	v_mfma_f32_16x16x32_bf16 v[100:103], v[228:231], v[192:195], v[100:103]
	v_mfma_f32_16x16x32_bf16 v[92:95], v[220:223], v[200:203], v[92:95]
	v_mfma_f32_16x16x32_bf16 v[84:87], v[228:231], v[200:203], v[84:87]
	s_setprio 2
	s_barrier
	v_mfma_f32_16x16x32_bf16 v[76:79], v[220:223], v[212:215], v[76:79]
	v_mfma_f32_16x16x32_bf16 v[68:71], v[228:231], v[212:215], v[68:71]
	s_setprio 0
	s_mov_b32 m0, s27
	s_add_u32 s100, s40, 0x80
	s_addc_u32 s101, s41, 0
	ds_read_b128 v[180:183], v145 offset:16384
	ds_read_b128 v[184:187], v145 offset:17408
	ds_read_b128 v[188:191], v145 offset:18432
	ds_read_b128 v[192:195], v145 offset:19456
	ds_read_b128 v[196:199], v145 offset:20480
	ds_read_b128 v[200:203], v145 offset:21504
	ds_read_b128 v[208:211], v145 offset:22528
	ds_read_b128 v[212:215], v145 offset:23552
	global_load_lds_dwordx4 v136, s[40:41]
	s_mov_b32 m0, s48
	s_nop 0
	global_load_lds_dwordx4 v134, s[40:41]
	s_waitcnt vmcnt(10)
	s_barrier
	s_setprio 1
	s_waitcnt lgkmcnt(0)
	v_mfma_f32_16x16x32_bf16 v[64:67], v[146:149], v[180:183], v[64:67]
	v_mfma_f32_16x16x32_bf16 v[56:59], v[154:157], v[180:183], v[56:59]
	v_mfma_f32_16x16x32_bf16 v[48:51], v[146:149], v[188:191], v[48:51]
	v_mfma_f32_16x16x32_bf16 v[40:43], v[154:157], v[188:191], v[40:43]
	v_mfma_f32_16x16x32_bf16 v[32:35], v[146:149], v[196:199], v[32:35]
	v_mfma_f32_16x16x32_bf16 v[24:27], v[154:157], v[196:199], v[24:27]
	v_mfma_f32_16x16x32_bf16 v[16:19], v[146:149], v[208:211], v[16:19]
	v_mfma_f32_16x16x32_bf16 v[8:11], v[154:157], v[208:211], v[8:11]
	v_mfma_f32_16x16x32_bf16 v[64:67], v[150:153], v[184:187], v[64:67]
	v_mfma_f32_16x16x32_bf16 v[56:59], v[158:161], v[184:187], v[56:59]
	v_mfma_f32_16x16x32_bf16 v[48:51], v[150:153], v[192:195], v[48:51]
	v_mfma_f32_16x16x32_bf16 v[40:43], v[158:161], v[192:195], v[40:43]
	v_mfma_f32_16x16x32_bf16 v[32:35], v[150:153], v[200:203], v[32:35]
	v_mfma_f32_16x16x32_bf16 v[24:27], v[158:161], v[200:203], v[24:27]
	s_setprio 2
	s_barrier
	v_mfma_f32_16x16x32_bf16 v[16:19], v[150:153], v[212:215], v[16:19]
	v_mfma_f32_16x16x32_bf16 v[8:11], v[158:161], v[212:215], v[8:11]
	s_setprio 0
	ds_read_b128 v[146:149], v248 offset:32768
	ds_read_b128 v[150:153], v248 offset:33792
	ds_read_b128 v[154:157], v248 offset:34816
	ds_read_b128 v[158:161], v248 offset:35840
	s_add_u32 s60, s36, 0x80000
	s_addc_u32 s61, s37, 0
	s_add_i32 s62, s62, s47
	s_mov_b32 m0, s62
	s_nop 0
	global_load_lds_dwordx4 v2, s[60:61]
	s_add_i32 m0, s62, 0x2000
	s_nop 0
	global_load_lds_dwordx4 v132, s[60:61]
	s_waitcnt vmcnt(6)
	s_barrier
	s_setprio 1
	v_mfma_f32_16x16x32_bf16 v[60:63], v[216:219], v[180:183], v[60:63]
	v_mfma_f32_16x16x32_bf16 v[52:55], v[224:227], v[180:183], v[52:55]
	v_mfma_f32_16x16x32_bf16 v[44:47], v[216:219], v[188:191], v[44:47]
	v_mfma_f32_16x16x32_bf16 v[36:39], v[224:227], v[188:191], v[36:39]
	v_mfma_f32_16x16x32_bf16 v[28:31], v[216:219], v[196:199], v[28:31]
	v_mfma_f32_16x16x32_bf16 v[20:23], v[224:227], v[196:199], v[20:23]
	v_mfma_f32_16x16x32_bf16 v[12:15], v[216:219], v[208:211], v[12:15]
	v_mfma_f32_16x16x32_bf16 v[4:7], v[224:227], v[208:211], v[4:7]
	v_mfma_f32_16x16x32_bf16 v[60:63], v[220:223], v[184:187], v[60:63]
	v_mfma_f32_16x16x32_bf16 v[52:55], v[228:231], v[184:187], v[52:55]
	v_mfma_f32_16x16x32_bf16 v[44:47], v[220:223], v[192:195], v[44:47]
	v_mfma_f32_16x16x32_bf16 v[36:39], v[228:231], v[192:195], v[36:39]
	v_mfma_f32_16x16x32_bf16 v[28:31], v[220:223], v[200:203], v[28:31]
	v_mfma_f32_16x16x32_bf16 v[20:23], v[228:231], v[200:203], v[20:23]
	s_setprio 2
	s_barrier
	v_mfma_f32_16x16x32_bf16 v[12:15], v[220:223], v[212:215], v[12:15]
	v_mfma_f32_16x16x32_bf16 v[4:7], v[228:231], v[212:215], v[4:7]
	s_setprio 0
	s_add_i32 s60, 0, 0x18000
	s_add_u32 s40, s40, 0x80000
	s_addc_u32 s41, s41, 0
	s_mov_b32 m0, s49
	ds_read_b128 v[180:183], v145 offset:32768
	ds_read_b128 v[184:187], v145 offset:33792
	ds_read_b128 v[188:191], v145 offset:34816
	ds_read_b128 v[192:195], v145 offset:35840
	ds_read_b128 v[196:199], v145 offset:36864
	ds_read_b128 v[200:203], v145 offset:37888
	ds_read_b128 v[208:211], v145 offset:38912
	ds_read_b128 v[212:215], v145 offset:39936
	global_load_lds_dwordx4 v136, s[40:41]
	s_mov_b32 m0, s50
	s_nop 0
	global_load_lds_dwordx4 v134, s[40:41]
	s_waitcnt lgkmcnt(8)
	s_barrier
	s_setprio 1
	s_waitcnt lgkmcnt(0)
	v_mfma_f32_16x16x32_bf16 v[128:131], v[146:149], v[180:183], v[128:131]
	v_mfma_f32_16x16x32_bf16 v[120:123], v[154:157], v[180:183], v[120:123]
	v_mfma_f32_16x16x32_bf16 v[112:115], v[146:149], v[188:191], v[112:115]
	v_mfma_f32_16x16x32_bf16 v[104:107], v[154:157], v[188:191], v[104:107]
	v_mfma_f32_16x16x32_bf16 v[96:99], v[146:149], v[196:199], v[96:99]
	v_mfma_f32_16x16x32_bf16 v[88:91], v[154:157], v[196:199], v[88:91]
	v_mfma_f32_16x16x32_bf16 v[80:83], v[146:149], v[208:211], v[80:83]
	v_mfma_f32_16x16x32_bf16 v[72:75], v[154:157], v[208:211], v[72:75]
	v_mfma_f32_16x16x32_bf16 v[128:131], v[150:153], v[184:187], v[128:131]
	v_mfma_f32_16x16x32_bf16 v[120:123], v[158:161], v[184:187], v[120:123]
	v_mfma_f32_16x16x32_bf16 v[112:115], v[150:153], v[192:195], v[112:115]
	v_mfma_f32_16x16x32_bf16 v[104:107], v[158:161], v[192:195], v[104:107]
	v_mfma_f32_16x16x32_bf16 v[96:99], v[150:153], v[200:203], v[96:99]
	v_mfma_f32_16x16x32_bf16 v[88:91], v[158:161], v[200:203], v[88:91]
	s_setprio 2
	s_barrier
; #define PG8_STAGE(bufoff, gbase, voff) do { _Pragma("unroll") for (int _i = 0; _i < 2; ++_i) \
;     __builtin_amdgcn_global_load_lds((const unsigned*)((const char*)(gbase) + (voff)[_i]), (LAS unsigned*)(lds + (bufoff) + ldsw + _i * 8192), 16, 0, 0); } while (0)
; #define PG8_LDA(dst, b, h) do { _Pragma("unroll") for (int m = 0; m < 4; ++m) _Pragma("unroll") for (int k = 0; k < 2; ++k) dst[m][k] = *(const LAS bf16x8*)(lds + PG8_SA(b, h) + aoff + m * 2048 + k * 1024); } while (0)
; #define PG8_LDB(dst, b, h) do { _Pragma("unroll") for (int n = 0; n < 2; ++n) _Pragma("unroll") for (int k = 0; k < 2; ++k) dst[n][k] = *(const LAS bf16x8*)(lds + PG8_SB(b, h) + boff + n * 2048 + k * 1024); } while (0)
; #define PG8_MMA(ai, bj, At, Bt) do { __builtin_amdgcn_s_setprio(1); _Pragma("unroll") for (int m = 0; m < 4; ++m) _Pragma("unroll") for (int n = 0; n < 2; ++n) _Pragma("unroll") for (int k = 0; k < 2; ++k) \
;     acc[ai][bj][m][n] = __builtin_amdgcn_mfma_f32_16x16x32_bf16(Bt[n][k], At[m][k], acc[ai][bj][m][n], 0, 0, 0); __builtin_amdgcn_s_setprio(0); } while (0)
; #define PG8_WAIT_V(n) asm volatile("s_waitcnt vmcnt(" #n ")" ::: "memory")
; #define PG8_WAIT_L(n) asm volatile("s_waitcnt lgkmcnt(" #n ")" ::: "memory")
; #define PG8_BAR __builtin_amdgcn_s_barrier()
; #define PG8_SCHED __builtin_amdgcn_sched_barrier(0)
; template <class Epi>
; DI void gemm_phase(LAS unsigned char* lds, const Gemm g, const Epi& E) {
;     ...
;       PG8_WAIT_L(8); PG8_BAR; PG8_WAIT_L(0); PG8_MMA(0, 0, At, B0); PG8_BAR; PG8_SCHED;
;       PG8_LDB(B1, 1, 1); PG8_STAGE(PG8_SB(1, 0), b3, voffB);
;       PG8_BAR; PG8_WAIT_L(0); PG8_MMA(0, 1, At, B1); PG8_BAR;
;       PG8_LDA(At, 1, 1); PG8_STAGE(PG8_SA(1, 0), a3, voffA);
;       PG8_BAR; PG8_WAIT_L(0); PG8_MMA(1, 0, At, B0); PG8_BAR; PG8_SCHED;
;       PG8_STAGE(PG8_SB(1, 1), b3 + hstepB, voffB);
;       PG8_WAIT_V(6); PG8_BAR; PG8_MMA(1, 1, At, B1); PG8_BAR;
	v_mfma_f32_16x16x32_bf16 v[80:83], v[150:153], v[212:215], v[80:83]
	v_mfma_f32_16x16x32_bf16 v[72:75], v[158:161], v[212:215], v[72:75]
	s_setprio 0
	s_add_i32 s40, 0, 0x1c000
	s_add_i32 s41, s60, s47
	s_mov_b32 m0, s41
	ds_read_b128 v[216:219], v248 offset:49152
	ds_read_b128 v[220:223], v248 offset:50176
	ds_read_b128 v[224:227], v248 offset:51200
	ds_read_b128 v[228:231], v248 offset:52224
	global_load_lds_dwordx4 v2, s[98:99]
	s_add_i32 m0, s41, 0x2000
	s_nop 0
	global_load_lds_dwordx4 v132, s[98:99]
	s_barrier
	s_setprio 1
	s_waitcnt lgkmcnt(0)
	v_mfma_f32_16x16x32_bf16 v[124:127], v[216:219], v[180:183], v[124:127]
	v_mfma_f32_16x16x32_bf16 v[116:119], v[224:227], v[180:183], v[116:119]
	v_mfma_f32_16x16x32_bf16 v[108:111], v[216:219], v[188:191], v[108:111]
	v_mfma_f32_16x16x32_bf16 v[100:103], v[224:227], v[188:191], v[100:103]
	v_mfma_f32_16x16x32_bf16 v[92:95], v[216:219], v[196:199], v[92:95]
	v_mfma_f32_16x16x32_bf16 v[84:87], v[224:227], v[196:199], v[84:87]
	v_mfma_f32_16x16x32_bf16 v[76:79], v[216:219], v[208:211], v[76:79]
	v_mfma_f32_16x16x32_bf16 v[68:71], v[224:227], v[208:211], v[68:71]
	v_mfma_f32_16x16x32_bf16 v[124:127], v[220:223], v[184:187], v[124:127]
	v_mfma_f32_16x16x32_bf16 v[116:119], v[228:231], v[184:187], v[116:119]
	v_mfma_f32_16x16x32_bf16 v[108:111], v[220:223], v[192:195], v[108:111]
	v_mfma_f32_16x16x32_bf16 v[100:103], v[228:231], v[192:195], v[100:103]
	v_mfma_f32_16x16x32_bf16 v[92:95], v[220:223], v[200:203], v[92:95]
	v_mfma_f32_16x16x32_bf16 v[84:87], v[228:231], v[200:203], v[84:87]
	s_setprio 2
	s_barrier
	v_mfma_f32_16x16x32_bf16 v[76:79], v[220:223], v[212:215], v[76:79]
	v_mfma_f32_16x16x32_bf16 v[68:71], v[228:231], v[212:215], v[68:71]
	s_setprio 0
	s_mov_b32 m0, s51
	ds_read_b128 v[180:183], v145 offset:49152
	ds_read_b128 v[184:187], v145 offset:50176
	ds_read_b128 v[188:191], v145 offset:51200
	ds_read_b128 v[192:195], v145 offset:52224
	ds_read_b128 v[196:199], v145 offset:53248
	ds_read_b128 v[200:203], v145 offset:54272
	ds_read_b128 v[208:211], v145 offset:55296
	ds_read_b128 v[212:215], v145 offset:56320
	global_load_lds_dwordx4 v136, s[100:101]
	s_mov_b32 m0, s52
	s_nop 0
	global_load_lds_dwordx4 v134, s[100:101]
	s_waitcnt vmcnt(10)
	s_barrier
	s_setprio 1
	s_waitcnt lgkmcnt(0)
	v_mfma_f32_16x16x32_bf16 v[64:67], v[146:149], v[180:183], v[64:67]
	v_mfma_f32_16x16x32_bf16 v[56:59], v[154:157], v[180:183], v[56:59]
	v_mfma_f32_16x16x32_bf16 v[48:51], v[146:149], v[188:191], v[48:51]
	v_mfma_f32_16x16x32_bf16 v[40:43], v[154:157], v[188:191], v[40:43]
	v_mfma_f32_16x16x32_bf16 v[32:35], v[146:149], v[196:199], v[32:35]
	v_mfma_f32_16x16x32_bf16 v[24:27], v[154:157], v[196:199], v[24:27]
	v_mfma_f32_16x16x32_bf16 v[16:19], v[146:149], v[208:211], v[16:19]
	v_mfma_f32_16x16x32_bf16 v[8:11], v[154:157], v[208:211], v[8:11]
	v_mfma_f32_16x16x32_bf16 v[64:67], v[150:153], v[184:187], v[64:67]
	v_mfma_f32_16x16x32_bf16 v[56:59], v[158:161], v[184:187], v[56:59]
	v_mfma_f32_16x16x32_bf16 v[48:51], v[150:153], v[192:195], v[48:51]
	v_mfma_f32_16x16x32_bf16 v[40:43], v[158:161], v[192:195], v[40:43]
	v_mfma_f32_16x16x32_bf16 v[32:35], v[150:153], v[200:203], v[32:35]
	v_mfma_f32_16x16x32_bf16 v[24:27], v[158:161], v[200:203], v[24:27]
	s_setprio 2
	s_barrier
	v_mfma_f32_16x16x32_bf16 v[16:19], v[150:153], v[212:215], v[16:19]
	v_mfma_f32_16x16x32_bf16 v[8:11], v[158:161], v[212:215], v[8:11]
	s_setprio 0
	ds_read_b128 v[146:149], v248
	ds_read_b128 v[150:153], v248 offset:1024
	ds_read_b128 v[154:157], v248 offset:2048
	ds_read_b128 v[158:161], v248 offset:3072
	s_add_u32 s36, s36, 0x80080
	s_addc_u32 s37, s37, 0
	s_add_i32 s40, s40, s47
	s_mov_b32 m0, s40
	s_nop 0
	global_load_lds_dwordx4 v2, s[36:37]
	s_add_i32 m0, s40, 0x2000
	s_nop 0
	global_load_lds_dwordx4 v132, s[36:37]
	s_waitcnt vmcnt(6)
	s_barrier
	s_setprio 1
	v_mfma_f32_16x16x32_bf16 v[60:63], v[216:219], v[180:183], v[60:63]
	v_mfma_f32_16x16x32_bf16 v[52:55], v[224:227], v[180:183], v[52:55]
	v_mfma_f32_16x16x32_bf16 v[44:47], v[216:219], v[188:191], v[44:47]
	v_mfma_f32_16x16x32_bf16 v[36:39], v[224:227], v[188:191], v[36:39]
	v_mfma_f32_16x16x32_bf16 v[28:31], v[216:219], v[196:199], v[28:31]
	v_mfma_f32_16x16x32_bf16 v[20:23], v[224:227], v[196:199], v[20:23]
	v_mfma_f32_16x16x32_bf16 v[12:15], v[216:219], v[208:211], v[12:15]
	v_mfma_f32_16x16x32_bf16 v[4:7], v[224:227], v[208:211], v[4:7]
	v_mfma_f32_16x16x32_bf16 v[60:63], v[220:223], v[184:187], v[60:63]
	v_mfma_f32_16x16x32_bf16 v[52:55], v[228:231], v[184:187], v[52:55]
	v_mfma_f32_16x16x32_bf16 v[44:47], v[220:223], v[192:195], v[44:47]
	v_mfma_f32_16x16x32_bf16 v[36:39], v[228:231], v[192:195], v[36:39]
	v_mfma_f32_16x16x32_bf16 v[28:31], v[220:223], v[200:203], v[28:31]
	v_mfma_f32_16x16x32_bf16 v[20:23], v[228:231], v[200:203], v[20:23]
	s_setprio 2
	s_barrier
	v_mfma_f32_16x16x32_bf16 v[12:15], v[220:223], v[212:215], v[12:15]
	v_mfma_f32_16x16x32_bf16 v[4:7], v[228:231], v[212:215], v[4:7]
	s_setprio 0
	s_add_i32 s59, s59, 2
	s_add_u32 s30, s30, 0x100
	s_addc_u32 s31, s31, 0
	s_add_u32 s57, s57, 0x100
	s_addc_u32 s58, s58, 0
	s_cmp_gt_u32 s59, 29
	s_cbranch_scc0 .LBB0_190

; #define PG8_STAGE(bufoff, gbase, voff) do { _Pragma("unroll") for (int _i = 0; _i < 2; ++_i) \
;     __builtin_amdgcn_global_load_lds((const unsigned*)((const char*)(gbase) + (voff)[_i]), (LAS unsigned*)(lds + (bufoff) + ldsw + _i * 8192), 16, 0, 0); } while (0)
; #define PG8_LDA(dst, b, h) do { _Pragma("unroll") for (int m = 0; m < 4; ++m) _Pragma("unroll") for (int k = 0; k < 2; ++k) dst[m][k] = *(const LAS bf16x8*)(lds + PG8_SA(b, h) + aoff + m * 2048 + k * 1024); } while (0)
; #define PG8_LDB(dst, b, h) do { _Pragma("unroll") for (int n = 0; n < 2; ++n) _Pragma("unroll") for (int k = 0; k < 2; ++k) dst[n][k] = *(const LAS bf16x8*)(lds + PG8_SB(b, h) + boff + n * 2048 + k * 1024); } while (0)
; #define PG8_MMA(ai, bj, At, Bt) do { __builtin_amdgcn_s_setprio(1); _Pragma("unroll") for (int m = 0; m < 4; ++m) _Pragma("unroll") for (int n = 0; n < 2; ++n) _Pragma("unroll") for (int k = 0; k < 2; ++k) \
;     acc[ai][bj][m][n] = __builtin_amdgcn_mfma_f32_16x16x32_bf16(Bt[n][k], At[m][k], acc[ai][bj][m][n], 0, 0, 0); __builtin_amdgcn_s_setprio(0); } while (0)
; #define PG8_WAIT_L(n) asm volatile("s_waitcnt lgkmcnt(" #n ")" ::: "memory")
; #define PG8_BAR __builtin_amdgcn_s_barrier()
; #define PG8_SCHED __builtin_amdgcn_sched_barrier(0)
; template <class Epi>
; DI void gemm_phase(LAS unsigned char* lds, const Gemm g, const Epi& E) {
;     ...
;     const bool has_next = S.next(ui + 1, nxt);
;     const char* nA = has_next ? PG8_APTR(nxt) : cA; const char* nB = has_next ? (const char*)g.Bt + (size_t)nxt.pn * tstepB : cB;
;     for (int t = 0; t < nt; t += 2) {
;       const bool last = (t == nt - 2);
;       const char* a1 = cA + (size_t)(t + 1) * kstep;
;       const char* a2 = last ? nA : cA + (size_t)(t + 2) * kstep; const char* b2 = last ? nB : cB + (size_t)(t + 2) * kstep;
;       const char* a3 = a2 + kstep; const char* b3 = b2 + kstep;
;       PG8_LDB(B0, 0, 0); PG8_SCHED; PG8_LDA(At, 0, 0); PG8_STAGE(PG8_SA(1, 1), a1 + hstepA, voffA);
;       PG8_WAIT_L(8); PG8_BAR; PG8_WAIT_L(0); PG8_MMA(0, 0, At, B0); PG8_BAR; PG8_SCHED;
;       PG8_LDB(B1, 0, 1); PG8_STAGE(PG8_SB(0, 0), b2, voffB);
;       PG8_BAR; PG8_WAIT_L(0); PG8_MMA(0, 1, At, B1); PG8_BAR;
;       PG8_LDA(At, 0, 1); PG8_STAGE(PG8_SA(0, 0), a2, voffA);
;       PG8_BAR; PG8_WAIT_L(0); PG8_MMA(1, 0, At, B0); PG8_BAR; PG8_SCHED;
.LBB0_513:
	s_add_u32 s42, s58, 0x80
	s_addc_u32 s43, s59, 0
	s_add_u32 s58, s56, 0x100
	s_addc_u32 s59, s57, 0
	s_mov_b32 s44, 0
	v_add_u32_e32 v248, 0x10000, v193
	ds_read_b128 v[132:135], v248
	ds_read_b128 v[136:139], v248 offset:1024
	ds_read_b128 v[140:143], v248 offset:2048
	ds_read_b128 v[144:147], v248 offset:3072
	s_add_i32 m0, s64, 0xc000
	ds_read_b128 v[148:151], v195
	ds_read_b128 v[152:155], v195 offset:1024
	ds_read_b128 v[156:159], v195 offset:2048
	ds_read_b128 v[160:163], v195 offset:3072
	ds_read_b128 v[196:199], v195 offset:4096
	ds_read_b128 v[200:203], v195 offset:5120
	ds_read_b128 v[208:211], v195 offset:6144
	ds_read_b128 v[212:215], v195 offset:7168
	global_load_lds_dwordx4 v186, s[42:43]
	s_add_i32 m0, s64, 0xe000
	s_nop 0
	global_load_lds_dwordx4 v188, s[42:43]
	s_waitcnt lgkmcnt(8)
	s_barrier
	s_setprio 1
	s_waitcnt lgkmcnt(0)
	v_mfma_f32_16x16x32_bf16 v[128:131], v[132:135], v[148:151], 0
	s_add_i32 s78, s44, 2
	v_mfma_f32_16x16x32_bf16 v[124:127], v[140:143], v[148:151], 0
	s_add_u32 s56, s42, 0x80
	s_addc_u32 s45, s43, 0
	v_mfma_f32_16x16x32_bf16 v[116:119], v[132:135], v[156:159], 0
	s_add_i32 s79, 0, 0x10000
	v_mfma_f32_16x16x32_bf16 v[108:111], v[140:143], v[156:159], 0
	s_cmp_eq_u32 s72, s44
	s_cselect_b32 s44, s52, s56
	s_cselect_b32 s45, s53, s45
	s_cselect_b32 s57, s55, s59
	s_cselect_b32 s56, s54, s58
	v_mfma_f32_16x16x32_bf16 v[100:103], v[132:135], v[196:199], 0
	v_mfma_f32_16x16x32_bf16 v[92:95], v[140:143], v[196:199], 0
	v_mfma_f32_16x16x32_bf16 v[84:87], v[132:135], v[208:211], 0
	v_mfma_f32_16x16x32_bf16 v[76:79], v[140:143], v[208:211], 0
	v_mfma_f32_16x16x32_bf16 v[128:131], v[136:139], v[152:155], v[128:131]
	v_mfma_f32_16x16x32_bf16 v[124:127], v[144:147], v[152:155], v[124:127]
	v_mfma_f32_16x16x32_bf16 v[116:119], v[136:139], v[160:163], v[116:119]
	v_mfma_f32_16x16x32_bf16 v[108:111], v[144:147], v[160:163], v[108:111]
	v_mfma_f32_16x16x32_bf16 v[100:103], v[136:139], v[200:203], v[100:103]
	v_mfma_f32_16x16x32_bf16 v[92:95], v[144:147], v[200:203], v[92:95]
	s_setprio 2
	s_barrier
	v_mfma_f32_16x16x32_bf16 v[84:87], v[136:139], v[212:215], v[84:87]
	v_mfma_f32_16x16x32_bf16 v[76:79], v[144:147], v[212:215], v[76:79]
	s_setprio 0
	s_add_i32 s80, 0, 0x14000
	s_add_i32 s79, s79, s63
	ds_read_b128 v[216:219], v248 offset:16384
	ds_read_b128 v[220:223], v248 offset:17408
	ds_read_b128 v[224:227], v248 offset:18432
	ds_read_b128 v[228:231], v248 offset:19456
	s_add_u32 s98, s56, 0x80
	s_addc_u32 s99, s57, 0
	s_mov_b32 m0, s79
	s_nop 0
	global_load_lds_dwordx4 v2, s[56:57]
	s_add_i32 m0, s79, 0x2000
	s_nop 0
	global_load_lds_dwordx4 v184, s[56:57]
	s_barrier
	s_setprio 1
	s_waitcnt lgkmcnt(0)
	v_mfma_f32_16x16x32_bf16 v[120:123], v[216:219], v[148:151], 0
	v_mfma_f32_16x16x32_bf16 v[112:115], v[224:227], v[148:151], 0
	v_mfma_f32_16x16x32_bf16 v[104:107], v[216:219], v[156:159], 0
	v_mfma_f32_16x16x32_bf16 v[96:99], v[224:227], v[156:159], 0
	v_mfma_f32_16x16x32_bf16 v[88:91], v[216:219], v[196:199], 0
	v_mfma_f32_16x16x32_bf16 v[80:83], v[224:227], v[196:199], 0
	v_mfma_f32_16x16x32_bf16 v[72:75], v[216:219], v[208:211], 0
	v_mfma_f32_16x16x32_bf16 v[68:71], v[224:227], v[208:211], 0
	v_mfma_f32_16x16x32_bf16 v[120:123], v[220:223], v[152:155], v[120:123]
	v_mfma_f32_16x16x32_bf16 v[112:115], v[228:231], v[152:155], v[112:115]
	v_mfma_f32_16x16x32_bf16 v[104:107], v[220:223], v[160:163], v[104:107]
	v_mfma_f32_16x16x32_bf16 v[96:99], v[228:231], v[160:163], v[96:99]
	v_mfma_f32_16x16x32_bf16 v[88:91], v[220:223], v[200:203], v[88:91]
	v_mfma_f32_16x16x32_bf16 v[80:83], v[228:231], v[200:203], v[80:83]
	s_setprio 2
	s_barrier
	v_mfma_f32_16x16x32_bf16 v[72:75], v[220:223], v[212:215], v[72:75]
	v_mfma_f32_16x16x32_bf16 v[68:71], v[228:231], v[212:215], v[68:71]
	s_setprio 0
	s_mov_b32 m0, s64
	s_add_u32 s100, s44, 0x80
	s_addc_u32 s101, s45, 0
	ds_read_b128 v[148:151], v195 offset:16384
	ds_read_b128 v[152:155], v195 offset:17408
	ds_read_b128 v[156:159], v195 offset:18432
	ds_read_b128 v[160:163], v195 offset:19456
	ds_read_b128 v[196:199], v195 offset:20480
	ds_read_b128 v[200:203], v195 offset:21504
	ds_read_b128 v[208:211], v195 offset:22528
	ds_read_b128 v[212:215], v195 offset:23552
	global_load_lds_dwordx4 v180, s[44:45]
	s_mov_b32 m0, s65
	s_nop 0
	global_load_lds_dwordx4 v182, s[44:45]
	s_waitcnt vmcnt(10)
	s_barrier
	s_setprio 1
	s_waitcnt lgkmcnt(0)
	v_mfma_f32_16x16x32_bf16 v[64:67], v[132:135], v[148:151], 0
	v_mfma_f32_16x16x32_bf16 v[60:63], v[140:143], v[148:151], 0
	v_mfma_f32_16x16x32_bf16 v[56:59], v[132:135], v[156:159], 0
	v_mfma_f32_16x16x32_bf16 v[48:51], v[140:143], v[156:159], 0
	v_mfma_f32_16x16x32_bf16 v[40:43], v[132:135], v[196:199], 0
	v_mfma_f32_16x16x32_bf16 v[32:35], v[140:143], v[196:199], 0
	v_mfma_f32_16x16x32_bf16 v[24:27], v[132:135], v[208:211], 0
	v_mfma_f32_16x16x32_bf16 v[16:19], v[140:143], v[208:211], 0
	v_mfma_f32_16x16x32_bf16 v[64:67], v[136:139], v[152:155], v[64:67]
	v_mfma_f32_16x16x32_bf16 v[60:63], v[144:147], v[152:155], v[60:63]
	v_mfma_f32_16x16x32_bf16 v[56:59], v[136:139], v[160:163], v[56:59]
	v_mfma_f32_16x16x32_bf16 v[48:51], v[144:147], v[160:163], v[48:51]
	v_mfma_f32_16x16x32_bf16 v[40:43], v[136:139], v[200:203], v[40:43]
	v_mfma_f32_16x16x32_bf16 v[32:35], v[144:147], v[200:203], v[32:35]
	s_setprio 2
	s_barrier
; #define PG8_STAGE(bufoff, gbase, voff) do { _Pragma("unroll") for (int _i = 0; _i < 2; ++_i) \
;     __builtin_amdgcn_global_load_lds((const unsigned*)((const char*)(gbase) + (voff)[_i]), (LAS unsigned*)(lds + (bufoff) + ldsw + _i * 8192), 16, 0, 0); } while (0)
; #define PG8_LDA(dst, b, h) do { _Pragma("unroll") for (int m = 0; m < 4; ++m) _Pragma("unroll") for (int k = 0; k < 2; ++k) dst[m][k] = *(const LAS bf16x8*)(lds + PG8_SA(b, h) + aoff + m * 2048 + k * 1024); } while (0)
; #define PG8_LDB(dst, b, h) do { _Pragma("unroll") for (int n = 0; n < 2; ++n) _Pragma("unroll") for (int k = 0; k < 2; ++k) dst[n][k] = *(const LAS bf16x8*)(lds + PG8_SB(b, h) + boff + n * 2048 + k * 1024); } while (0)
; #define PG8_MMA(ai, bj, At, Bt) do { __builtin_amdgcn_s_setprio(1); _Pragma("unroll") for (int m = 0; m < 4; ++m) _Pragma("unroll") for (int n = 0; n < 2; ++n) _Pragma("unroll") for (int k = 0; k < 2; ++k) \
;     acc[ai][bj][m][n] = __builtin_amdgcn_mfma_f32_16x16x32_bf16(Bt[n][k], At[m][k], acc[ai][bj][m][n], 0, 0, 0); __builtin_amdgcn_s_setprio(0); } while (0)
; #define PG8_WAIT_V(n) asm volatile("s_waitcnt vmcnt(" #n ")" ::: "memory")
; #define PG8_WAIT_L(n) asm volatile("s_waitcnt lgkmcnt(" #n ")" ::: "memory")
; #define PG8_BAR __builtin_amdgcn_s_barrier()
; #define PG8_SCHED __builtin_amdgcn_sched_barrier(0)
; template <class Epi>
; DI void gemm_phase(LAS unsigned char* lds, const Gemm g, const Epi& E) {
;     ...
;       PG8_STAGE(PG8_SB(0, 1), b2 + hstepB, voffB);
;       PG8_WAIT_V(6); PG8_BAR; PG8_MMA(1, 1, At, B1); PG8_BAR;
;       PG8_LDB(B0, 1, 0); PG8_SCHED; PG8_LDA(At, 1, 0); PG8_STAGE(PG8_SA(0, 1), a2 + hstepA, voffA);
;       PG8_WAIT_L(8); PG8_BAR; PG8_WAIT_L(0); PG8_MMA(0, 0, At, B0); PG8_BAR; PG8_SCHED;
;       PG8_LDB(B1, 1, 1); PG8_STAGE(PG8_SB(1, 0), b3, voffB);
;       PG8_BAR; PG8_WAIT_L(0); PG8_MMA(0, 1, At, B1); PG8_BAR;
;       PG8_LDA(At, 1, 1); PG8_STAGE(PG8_SA(1, 0), a3, voffA);
;       PG8_BAR; PG8_WAIT_L(0); PG8_MMA(1, 0, At, B0); PG8_BAR; PG8_SCHED;
	v_mfma_f32_16x16x32_bf16 v[24:27], v[136:139], v[212:215], v[24:27]
	v_mfma_f32_16x16x32_bf16 v[16:19], v[144:147], v[212:215], v[16:19]
	s_setprio 0
	ds_read_b128 v[132:135], v248 offset:32768
	ds_read_b128 v[136:139], v248 offset:33792
	ds_read_b128 v[140:143], v248 offset:34816
	ds_read_b128 v[144:147], v248 offset:35840
	s_add_u32 s56, s56, s18
	s_addc_u32 s57, s57, s19
	s_add_i32 s79, s80, s63
	v_lshl_add_u64 v[238:239], s[56:57], 0, v[2:3]
	s_mov_b32 m0, s79
	v_lshl_add_u64 v[240:241], s[56:57], 0, v[184:185]
	global_load_lds_dwordx4 v[238:239], off
	s_add_i32 m0, s79, 0x2000
	s_nop 0
	global_load_lds_dwordx4 v[240:241], off
	s_waitcnt vmcnt(6)
	s_barrier
	s_setprio 1
	v_mfma_f32_16x16x32_bf16 v[52:55], v[216:219], v[148:151], 0
	v_mfma_f32_16x16x32_bf16 v[44:47], v[224:227], v[148:151], 0
	v_mfma_f32_16x16x32_bf16 v[36:39], v[216:219], v[156:159], 0
	v_mfma_f32_16x16x32_bf16 v[28:31], v[224:227], v[156:159], 0
	v_mfma_f32_16x16x32_bf16 v[20:23], v[216:219], v[196:199], 0
	v_mfma_f32_16x16x32_bf16 v[12:15], v[224:227], v[196:199], 0
	v_mfma_f32_16x16x32_bf16 v[8:11], v[216:219], v[208:211], 0
	v_mfma_f32_16x16x32_bf16 v[4:7], v[224:227], v[208:211], 0
	v_mfma_f32_16x16x32_bf16 v[52:55], v[220:223], v[152:155], v[52:55]
	v_mfma_f32_16x16x32_bf16 v[44:47], v[228:231], v[152:155], v[44:47]
	v_mfma_f32_16x16x32_bf16 v[36:39], v[220:223], v[160:163], v[36:39]
	v_mfma_f32_16x16x32_bf16 v[28:31], v[228:231], v[160:163], v[28:31]
	v_mfma_f32_16x16x32_bf16 v[20:23], v[220:223], v[200:203], v[20:23]
	v_mfma_f32_16x16x32_bf16 v[12:15], v[228:231], v[200:203], v[12:15]
	s_setprio 2
	s_barrier
	v_mfma_f32_16x16x32_bf16 v[8:11], v[220:223], v[212:215], v[8:11]
	v_mfma_f32_16x16x32_bf16 v[4:7], v[228:231], v[212:215], v[4:7]
	s_setprio 0
	s_add_i32 s56, 0, 0x18000
	s_add_u32 s44, s44, s8
	s_addc_u32 s45, s45, 0
	s_mov_b32 m0, s66
	ds_read_b128 v[148:151], v195 offset:32768
	ds_read_b128 v[152:155], v195 offset:33792
	ds_read_b128 v[156:159], v195 offset:34816
	ds_read_b128 v[160:163], v195 offset:35840
	ds_read_b128 v[196:199], v195 offset:36864
	ds_read_b128 v[200:203], v195 offset:37888
	ds_read_b128 v[208:211], v195 offset:38912
	ds_read_b128 v[212:215], v195 offset:39936
	global_load_lds_dwordx4 v180, s[44:45]
	s_mov_b32 m0, s67
	s_nop 0
	global_load_lds_dwordx4 v182, s[44:45]
	s_waitcnt lgkmcnt(8)
	s_barrier
	s_setprio 1
	s_waitcnt lgkmcnt(0)
	v_mfma_f32_16x16x32_bf16 v[128:131], v[132:135], v[148:151], v[128:131]
	v_mfma_f32_16x16x32_bf16 v[124:127], v[140:143], v[148:151], v[124:127]
	v_mfma_f32_16x16x32_bf16 v[116:119], v[132:135], v[156:159], v[116:119]
	v_mfma_f32_16x16x32_bf16 v[108:111], v[140:143], v[156:159], v[108:111]
	v_mfma_f32_16x16x32_bf16 v[100:103], v[132:135], v[196:199], v[100:103]
	v_mfma_f32_16x16x32_bf16 v[92:95], v[140:143], v[196:199], v[92:95]
	v_mfma_f32_16x16x32_bf16 v[84:87], v[132:135], v[208:211], v[84:87]
	v_mfma_f32_16x16x32_bf16 v[76:79], v[140:143], v[208:211], v[76:79]
	v_mfma_f32_16x16x32_bf16 v[128:131], v[136:139], v[152:155], v[128:131]
	v_mfma_f32_16x16x32_bf16 v[124:127], v[144:147], v[152:155], v[124:127]
	v_mfma_f32_16x16x32_bf16 v[116:119], v[136:139], v[160:163], v[116:119]
	v_mfma_f32_16x16x32_bf16 v[108:111], v[144:147], v[160:163], v[108:111]
	v_mfma_f32_16x16x32_bf16 v[100:103], v[136:139], v[200:203], v[100:103]
	v_mfma_f32_16x16x32_bf16 v[92:95], v[144:147], v[200:203], v[92:95]
	s_setprio 2
	s_barrier
	v_mfma_f32_16x16x32_bf16 v[84:87], v[136:139], v[212:215], v[84:87]
	v_mfma_f32_16x16x32_bf16 v[76:79], v[144:147], v[212:215], v[76:79]
	s_setprio 0
	s_add_i32 s44, 0, 0x1c000
	s_add_i32 s45, s56, s63
	s_mov_b32 m0, s45
	ds_read_b128 v[216:219], v248 offset:49152
	ds_read_b128 v[220:223], v248 offset:50176
	ds_read_b128 v[224:227], v248 offset:51200
	ds_read_b128 v[228:231], v248 offset:52224
	global_load_lds_dwordx4 v2, s[98:99]
	s_add_i32 m0, s45, 0x2000
	s_nop 0
	global_load_lds_dwordx4 v184, s[98:99]
	s_barrier
	s_setprio 1
	s_waitcnt lgkmcnt(0)
	v_mfma_f32_16x16x32_bf16 v[120:123], v[216:219], v[148:151], v[120:123]
	v_mfma_f32_16x16x32_bf16 v[112:115], v[224:227], v[148:151], v[112:115]
	v_mfma_f32_16x16x32_bf16 v[104:107], v[216:219], v[156:159], v[104:107]
	v_mfma_f32_16x16x32_bf16 v[96:99], v[224:227], v[156:159], v[96:99]
	v_mfma_f32_16x16x32_bf16 v[88:91], v[216:219], v[196:199], v[88:91]
	v_mfma_f32_16x16x32_bf16 v[80:83], v[224:227], v[196:199], v[80:83]
	v_mfma_f32_16x16x32_bf16 v[72:75], v[216:219], v[208:211], v[72:75]
	v_mfma_f32_16x16x32_bf16 v[68:71], v[224:227], v[208:211], v[68:71]
	v_mfma_f32_16x16x32_bf16 v[120:123], v[220:223], v[152:155], v[120:123]
	v_mfma_f32_16x16x32_bf16 v[112:115], v[228:231], v[152:155], v[112:115]
	v_mfma_f32_16x16x32_bf16 v[104:107], v[220:223], v[160:163], v[104:107]
	v_mfma_f32_16x16x32_bf16 v[96:99], v[228:231], v[160:163], v[96:99]
	v_mfma_f32_16x16x32_bf16 v[88:91], v[220:223], v[200:203], v[88:91]
	v_mfma_f32_16x16x32_bf16 v[80:83], v[228:231], v[200:203], v[80:83]
	s_setprio 2
	s_barrier
	v_mfma_f32_16x16x32_bf16 v[72:75], v[220:223], v[212:215], v[72:75]
	v_mfma_f32_16x16x32_bf16 v[68:71], v[228:231], v[212:215], v[68:71]
	s_setprio 0
	s_mov_b32 m0, s69
	ds_read_b128 v[148:151], v195 offset:49152
	ds_read_b128 v[152:155], v195 offset:50176
	ds_read_b128 v[156:159], v195 offset:51200
	ds_read_b128 v[160:163], v195 offset:52224
	ds_read_b128 v[196:199], v195 offset:53248
	ds_read_b128 v[200:203], v195 offset:54272
	ds_read_b128 v[208:211], v195 offset:55296
	ds_read_b128 v[212:215], v195 offset:56320
	global_load_lds_dwordx4 v180, s[100:101]
	s_mov_b32 m0, s71
	s_nop 0
	global_load_lds_dwordx4 v182, s[100:101]
	s_waitcnt vmcnt(10)
	s_barrier
; #define PG8_STAGE(bufoff, gbase, voff) do { _Pragma("unroll") for (int _i = 0; _i < 2; ++_i) \
;     __builtin_amdgcn_global_load_lds((const unsigned*)((const char*)(gbase) + (voff)[_i]), (LAS unsigned*)(lds + (bufoff) + ldsw + _i * 8192), 16, 0, 0); } while (0)
; #define PG8_LDA(dst, b, h) do { _Pragma("unroll") for (int m = 0; m < 4; ++m) _Pragma("unroll") for (int k = 0; k < 2; ++k) dst[m][k] = *(const LAS bf16x8*)(lds + PG8_SA(b, h) + aoff + m * 2048 + k * 1024); } while (0)
; #define PG8_LDB(dst, b, h) do { _Pragma("unroll") for (int n = 0; n < 2; ++n) _Pragma("unroll") for (int k = 0; k < 2; ++k) dst[n][k] = *(const LAS bf16x8*)(lds + PG8_SB(b, h) + boff + n * 2048 + k * 1024); } while (0)
; #define PG8_MMA(ai, bj, At, Bt) do { __builtin_amdgcn_s_setprio(1); _Pragma("unroll") for (int m = 0; m < 4; ++m) _Pragma("unroll") for (int n = 0; n < 2; ++n) _Pragma("unroll") for (int k = 0; k < 2; ++k) \
;     acc[ai][bj][m][n] = __builtin_amdgcn_mfma_f32_16x16x32_bf16(Bt[n][k], At[m][k], acc[ai][bj][m][n], 0, 0, 0); __builtin_amdgcn_s_setprio(0); } while (0)
; #define PG8_WAIT_V(n) asm volatile("s_waitcnt vmcnt(" #n ")" ::: "memory")
; #define PG8_WAIT_L(n) asm volatile("s_waitcnt lgkmcnt(" #n ")" ::: "memory")
; #define PG8_BAR __builtin_amdgcn_s_barrier()
; #define PG8_SCHED __builtin_amdgcn_sched_barrier(0)
; template <class Epi>
; DI void gemm_phase(LAS unsigned char* lds, const Gemm g, const Epi& E) {
;     ...
;       PG8_LDB(B0, 0, 0); PG8_SCHED; PG8_LDA(At, 0, 0); PG8_STAGE(PG8_SA(1, 1), a1 + hstepA, voffA);
;       PG8_WAIT_L(8); PG8_BAR; PG8_WAIT_L(0); PG8_MMA(0, 0, At, B0); PG8_BAR; PG8_SCHED;
;       PG8_LDB(B1, 0, 1); PG8_STAGE(PG8_SB(0, 0), b2, voffB);
;       PG8_BAR; PG8_WAIT_L(0); PG8_MMA(0, 1, At, B1); PG8_BAR;
;     ...
;       PG8_BAR; PG8_WAIT_L(0); PG8_MMA(1, 0, At, B0); PG8_BAR; PG8_SCHED;
;       PG8_STAGE(PG8_SB(1, 1), b3 + hstepB, voffB);
;       PG8_WAIT_V(6); PG8_BAR; PG8_MMA(1, 1, At, B1); PG8_BAR;
	s_setprio 1
	s_waitcnt lgkmcnt(0)
	v_mfma_f32_16x16x32_bf16 v[64:67], v[132:135], v[148:151], v[64:67]
	v_mfma_f32_16x16x32_bf16 v[60:63], v[140:143], v[148:151], v[60:63]
	v_mfma_f32_16x16x32_bf16 v[56:59], v[132:135], v[156:159], v[56:59]
	v_mfma_f32_16x16x32_bf16 v[48:51], v[140:143], v[156:159], v[48:51]
	v_mfma_f32_16x16x32_bf16 v[40:43], v[132:135], v[196:199], v[40:43]
	v_mfma_f32_16x16x32_bf16 v[32:35], v[140:143], v[196:199], v[32:35]
	v_mfma_f32_16x16x32_bf16 v[24:27], v[132:135], v[208:211], v[24:27]
	v_mfma_f32_16x16x32_bf16 v[16:19], v[140:143], v[208:211], v[16:19]
	v_mfma_f32_16x16x32_bf16 v[64:67], v[136:139], v[152:155], v[64:67]
	v_mfma_f32_16x16x32_bf16 v[60:63], v[144:147], v[152:155], v[60:63]
	v_mfma_f32_16x16x32_bf16 v[56:59], v[136:139], v[160:163], v[56:59]
	v_mfma_f32_16x16x32_bf16 v[48:51], v[144:147], v[160:163], v[48:51]
	v_mfma_f32_16x16x32_bf16 v[40:43], v[136:139], v[200:203], v[40:43]
	v_mfma_f32_16x16x32_bf16 v[32:35], v[144:147], v[200:203], v[32:35]
	s_setprio 2
	s_barrier
	v_mfma_f32_16x16x32_bf16 v[24:27], v[136:139], v[212:215], v[24:27]
	v_mfma_f32_16x16x32_bf16 v[16:19], v[144:147], v[212:215], v[16:19]
	s_setprio 0
	ds_read_b128 v[132:135], v248
	ds_read_b128 v[136:139], v248 offset:1024
	ds_read_b128 v[140:143], v248 offset:2048
	ds_read_b128 v[144:147], v248 offset:3072
	s_add_i32 s44, s44, s63
	v_lshl_add_u64 v[246:247], v[238:239], 0, s[84:85]
	s_mov_b32 m0, s44
	s_nop 0
	global_load_lds_dwordx4 v[246:247], off
	v_lshl_add_u64 v[246:247], v[240:241], 0, s[84:85]
	s_add_i32 m0, s44, 0x2000
	s_nop 0
	global_load_lds_dwordx4 v[246:247], off
	s_waitcnt vmcnt(6)
	s_barrier
	s_setprio 1
	v_mfma_f32_16x16x32_bf16 v[52:55], v[216:219], v[148:151], v[52:55]
	v_mfma_f32_16x16x32_bf16 v[44:47], v[224:227], v[148:151], v[44:47]
	v_mfma_f32_16x16x32_bf16 v[36:39], v[216:219], v[156:159], v[36:39]
	v_mfma_f32_16x16x32_bf16 v[28:31], v[224:227], v[156:159], v[28:31]
	v_mfma_f32_16x16x32_bf16 v[20:23], v[216:219], v[196:199], v[20:23]
	v_mfma_f32_16x16x32_bf16 v[12:15], v[224:227], v[196:199], v[12:15]
	v_mfma_f32_16x16x32_bf16 v[8:11], v[216:219], v[208:211], v[8:11]
	v_mfma_f32_16x16x32_bf16 v[4:7], v[224:227], v[208:211], v[4:7]
	v_mfma_f32_16x16x32_bf16 v[52:55], v[220:223], v[152:155], v[52:55]
	v_mfma_f32_16x16x32_bf16 v[44:47], v[228:231], v[152:155], v[44:47]
	v_mfma_f32_16x16x32_bf16 v[36:39], v[220:223], v[160:163], v[36:39]
	v_mfma_f32_16x16x32_bf16 v[28:31], v[228:231], v[160:163], v[28:31]
	v_mfma_f32_16x16x32_bf16 v[20:23], v[220:223], v[200:203], v[20:23]
	v_mfma_f32_16x16x32_bf16 v[12:15], v[228:231], v[200:203], v[12:15]
	s_setprio 2
	s_barrier
	v_mfma_f32_16x16x32_bf16 v[8:11], v[220:223], v[212:215], v[8:11]
	v_mfma_f32_16x16x32_bf16 v[4:7], v[228:231], v[212:215], v[4:7]
	s_setprio 0
	s_add_u32 s42, s42, 0x100
	s_addc_u32 s43, s43, 0
	s_add_u32 s58, s58, 0x100
	s_addc_u32 s59, s59, 0
	s_cmp_ge_u32 s78, s68
	s_mov_b32 s44, s78
	s_cbranch_scc1 .Lpeel_exit_514
.LBB0_514:
	s_add_i32 m0, s64, 0xc000
	ds_read_b128 v[148:151], v195
	ds_read_b128 v[152:155], v195 offset:1024
	ds_read_b128 v[156:159], v195 offset:2048
	ds_read_b128 v[160:163], v195 offset:3072
	ds_read_b128 v[196:199], v195 offset:4096
	ds_read_b128 v[200:203], v195 offset:5120
	ds_read_b128 v[208:211], v195 offset:6144
	ds_read_b128 v[212:215], v195 offset:7168
	global_load_lds_dwordx4 v186, s[42:43]
	s_add_i32 m0, s64, 0xe000
	s_nop 0
	global_load_lds_dwordx4 v188, s[42:43]
	s_waitcnt lgkmcnt(8)
	s_barrier
	s_setprio 1
	s_waitcnt lgkmcnt(0)
	v_mfma_f32_16x16x32_bf16 v[128:131], v[132:135], v[148:151], v[128:131]
	s_add_i32 s78, s44, 2
	v_mfma_f32_16x16x32_bf16 v[124:127], v[140:143], v[148:151], v[124:127]
	s_add_u32 s56, s42, 0x80
	s_addc_u32 s45, s43, 0
	v_mfma_f32_16x16x32_bf16 v[116:119], v[132:135], v[156:159], v[116:119]
	s_add_i32 s79, 0, 0x10000
	v_mfma_f32_16x16x32_bf16 v[108:111], v[140:143], v[156:159], v[108:111]
	s_cmp_eq_u32 s72, s44
	s_cselect_b32 s44, s52, s56
	s_cselect_b32 s45, s53, s45
	s_cselect_b32 s57, s55, s59
	s_cselect_b32 s56, s54, s58
	v_mfma_f32_16x16x32_bf16 v[100:103], v[132:135], v[196:199], v[100:103]
	v_mfma_f32_16x16x32_bf16 v[92:95], v[140:143], v[196:199], v[92:95]
	v_mfma_f32_16x16x32_bf16 v[84:87], v[132:135], v[208:211], v[84:87]
	v_mfma_f32_16x16x32_bf16 v[76:79], v[140:143], v[208:211], v[76:79]
	v_mfma_f32_16x16x32_bf16 v[128:131], v[136:139], v[152:155], v[128:131]
	v_mfma_f32_16x16x32_bf16 v[124:127], v[144:147], v[152:155], v[124:127]
	v_mfma_f32_16x16x32_bf16 v[116:119], v[136:139], v[160:163], v[116:119]
	v_mfma_f32_16x16x32_bf16 v[108:111], v[144:147], v[160:163], v[108:111]
	v_mfma_f32_16x16x32_bf16 v[100:103], v[136:139], v[200:203], v[100:103]
	v_mfma_f32_16x16x32_bf16 v[92:95], v[144:147], v[200:203], v[92:95]
	s_setprio 2
	s_barrier
	v_mfma_f32_16x16x32_bf16 v[84:87], v[136:139], v[212:215], v[84:87]
	v_mfma_f32_16x16x32_bf16 v[76:79], v[144:147], v[212:215], v[76:79]
	s_setprio 0
	s_add_i32 s80, 0, 0x14000
	s_add_i32 s79, s79, s63
	ds_read_b128 v[216:219], v248 offset:16384
	ds_read_b128 v[220:223], v248 offset:17408
	ds_read_b128 v[224:227], v248 offset:18432
	ds_read_b128 v[228:231], v248 offset:19456
	s_add_u32 s98, s56, 0x80
	s_addc_u32 s99, s57, 0
	s_mov_b32 m0, s79
	s_nop 0
	global_load_lds_dwordx4 v2, s[56:57]
	s_add_i32 m0, s79, 0x2000
	s_nop 0
	global_load_lds_dwordx4 v184, s[56:57]
	s_barrier
; #define PG8_STAGE(bufoff, gbase, voff) do { _Pragma("unroll") for (int _i = 0; _i < 2; ++_i) \
;     __builtin_amdgcn_global_load_lds((const unsigned*)((const char*)(gbase) + (voff)[_i]), (LAS unsigned*)(lds + (bufoff) + ldsw + _i * 8192), 16, 0, 0); } while (0)
; #define PG8_LDA(dst, b, h) do { _Pragma("unroll") for (int m = 0; m < 4; ++m) _Pragma("unroll") for (int k = 0; k < 2; ++k) dst[m][k] = *(const LAS bf16x8*)(lds + PG8_SA(b, h) + aoff + m * 2048 + k * 1024); } while (0)
; #define PG8_LDB(dst, b, h) do { _Pragma("unroll") for (int n = 0; n < 2; ++n) _Pragma("unroll") for (int k = 0; k < 2; ++k) dst[n][k] = *(const LAS bf16x8*)(lds + PG8_SB(b, h) + boff + n * 2048 + k * 1024); } while (0)
; #define PG8_MMA(ai, bj, At, Bt) do { __builtin_amdgcn_s_setprio(1); _Pragma("unroll") for (int m = 0; m < 4; ++m) _Pragma("unroll") for (int n = 0; n < 2; ++n) _Pragma("unroll") for (int k = 0; k < 2; ++k) \
;     acc[ai][bj][m][n] = __builtin_amdgcn_mfma_f32_16x16x32_bf16(Bt[n][k], At[m][k], acc[ai][bj][m][n], 0, 0, 0); __builtin_amdgcn_s_setprio(0); } while (0)
; #define PG8_WAIT_V(n) asm volatile("s_waitcnt vmcnt(" #n ")" ::: "memory")
; #define PG8_WAIT_L(n) asm volatile("s_waitcnt lgkmcnt(" #n ")" ::: "memory")
; #define PG8_BAR __builtin_amdgcn_s_barrier()
; #define PG8_SCHED __builtin_amdgcn_sched_barrier(0)
; template <class Epi>
; DI void gemm_phase(LAS unsigned char* lds, const Gemm g, const Epi& E) {
;     ...
;       PG8_BAR; PG8_WAIT_L(0); PG8_MMA(0, 1, At, B1); PG8_BAR;
;       PG8_LDA(At, 0, 1); PG8_STAGE(PG8_SA(0, 0), a2, voffA);
;       PG8_BAR; PG8_WAIT_L(0); PG8_MMA(1, 0, At, B0); PG8_BAR; PG8_SCHED;
;       PG8_STAGE(PG8_SB(0, 1), b2 + hstepB, voffB);
;       PG8_WAIT_V(6); PG8_BAR; PG8_MMA(1, 1, At, B1); PG8_BAR;
;       PG8_LDB(B0, 1, 0); PG8_SCHED; PG8_LDA(At, 1, 0); PG8_STAGE(PG8_SA(0, 1), a2 + hstepA, voffA);
;       PG8_WAIT_L(8); PG8_BAR; PG8_WAIT_L(0); PG8_MMA(0, 0, At, B0); PG8_BAR; PG8_SCHED;
;       PG8_LDB(B1, 1, 1); PG8_STAGE(PG8_SB(1, 0), b3, voffB);
;       PG8_BAR; PG8_WAIT_L(0); PG8_MMA(0, 1, At, B1); PG8_BAR;
;       PG8_LDA(At, 1, 1); PG8_STAGE(PG8_SA(1, 0), a3, voffA);
;       PG8_BAR; PG8_WAIT_L(0); PG8_MMA(1, 0, At, B0); PG8_BAR; PG8_SCHED;
	s_setprio 1
	s_waitcnt lgkmcnt(0)
	v_mfma_f32_16x16x32_bf16 v[120:123], v[216:219], v[148:151], v[120:123]
	v_mfma_f32_16x16x32_bf16 v[112:115], v[224:227], v[148:151], v[112:115]
	v_mfma_f32_16x16x32_bf16 v[104:107], v[216:219], v[156:159], v[104:107]
	v_mfma_f32_16x16x32_bf16 v[96:99], v[224:227], v[156:159], v[96:99]
	v_mfma_f32_16x16x32_bf16 v[88:91], v[216:219], v[196:199], v[88:91]
	v_mfma_f32_16x16x32_bf16 v[80:83], v[224:227], v[196:199], v[80:83]
	v_mfma_f32_16x16x32_bf16 v[72:75], v[216:219], v[208:211], v[72:75]
	v_mfma_f32_16x16x32_bf16 v[68:71], v[224:227], v[208:211], v[68:71]
	v_mfma_f32_16x16x32_bf16 v[120:123], v[220:223], v[152:155], v[120:123]
	v_mfma_f32_16x16x32_bf16 v[112:115], v[228:231], v[152:155], v[112:115]
	v_mfma_f32_16x16x32_bf16 v[104:107], v[220:223], v[160:163], v[104:107]
	v_mfma_f32_16x16x32_bf16 v[96:99], v[228:231], v[160:163], v[96:99]
	v_mfma_f32_16x16x32_bf16 v[88:91], v[220:223], v[200:203], v[88:91]
	v_mfma_f32_16x16x32_bf16 v[80:83], v[228:231], v[200:203], v[80:83]
	s_setprio 2
	s_barrier
	v_mfma_f32_16x16x32_bf16 v[72:75], v[220:223], v[212:215], v[72:75]
	v_mfma_f32_16x16x32_bf16 v[68:71], v[228:231], v[212:215], v[68:71]
	s_setprio 0
	s_mov_b32 m0, s64
	s_add_u32 s100, s44, 0x80
	s_addc_u32 s101, s45, 0
	ds_read_b128 v[148:151], v195 offset:16384
	ds_read_b128 v[152:155], v195 offset:17408
	ds_read_b128 v[156:159], v195 offset:18432
	ds_read_b128 v[160:163], v195 offset:19456
	ds_read_b128 v[196:199], v195 offset:20480
	ds_read_b128 v[200:203], v195 offset:21504
	ds_read_b128 v[208:211], v195 offset:22528
	ds_read_b128 v[212:215], v195 offset:23552
	global_load_lds_dwordx4 v180, s[44:45]
	s_mov_b32 m0, s65
	s_nop 0
	global_load_lds_dwordx4 v182, s[44:45]
	s_waitcnt vmcnt(10)
	s_barrier
	s_setprio 1
	s_waitcnt lgkmcnt(0)
	v_mfma_f32_16x16x32_bf16 v[64:67], v[132:135], v[148:151], v[64:67]
	v_mfma_f32_16x16x32_bf16 v[60:63], v[140:143], v[148:151], v[60:63]
	v_mfma_f32_16x16x32_bf16 v[56:59], v[132:135], v[156:159], v[56:59]
	v_mfma_f32_16x16x32_bf16 v[48:51], v[140:143], v[156:159], v[48:51]
	v_mfma_f32_16x16x32_bf16 v[40:43], v[132:135], v[196:199], v[40:43]
	v_mfma_f32_16x16x32_bf16 v[32:35], v[140:143], v[196:199], v[32:35]
	v_mfma_f32_16x16x32_bf16 v[24:27], v[132:135], v[208:211], v[24:27]
	v_mfma_f32_16x16x32_bf16 v[16:19], v[140:143], v[208:211], v[16:19]
	v_mfma_f32_16x16x32_bf16 v[64:67], v[136:139], v[152:155], v[64:67]
	v_mfma_f32_16x16x32_bf16 v[60:63], v[144:147], v[152:155], v[60:63]
	v_mfma_f32_16x16x32_bf16 v[56:59], v[136:139], v[160:163], v[56:59]
	v_mfma_f32_16x16x32_bf16 v[48:51], v[144:147], v[160:163], v[48:51]
	v_mfma_f32_16x16x32_bf16 v[40:43], v[136:139], v[200:203], v[40:43]
	v_mfma_f32_16x16x32_bf16 v[32:35], v[144:147], v[200:203], v[32:35]
	s_setprio 2
	s_barrier
	v_mfma_f32_16x16x32_bf16 v[24:27], v[136:139], v[212:215], v[24:27]
	v_mfma_f32_16x16x32_bf16 v[16:19], v[144:147], v[212:215], v[16:19]
	s_setprio 0
	ds_read_b128 v[132:135], v248 offset:32768
	ds_read_b128 v[136:139], v248 offset:33792
	ds_read_b128 v[140:143], v248 offset:34816
	ds_read_b128 v[144:147], v248 offset:35840
	s_add_u32 s56, s56, s18
	s_addc_u32 s57, s57, s19
	s_add_i32 s79, s80, s63
	v_lshl_add_u64 v[238:239], s[56:57], 0, v[2:3]
	s_mov_b32 m0, s79
	v_lshl_add_u64 v[240:241], s[56:57], 0, v[184:185]
	global_load_lds_dwordx4 v[238:239], off
	s_add_i32 m0, s79, 0x2000
	s_nop 0
	global_load_lds_dwordx4 v[240:241], off
	s_waitcnt vmcnt(6)
	s_barrier
	s_setprio 1
	v_mfma_f32_16x16x32_bf16 v[52:55], v[216:219], v[148:151], v[52:55]
	v_mfma_f32_16x16x32_bf16 v[44:47], v[224:227], v[148:151], v[44:47]
	v_mfma_f32_16x16x32_bf16 v[36:39], v[216:219], v[156:159], v[36:39]
	v_mfma_f32_16x16x32_bf16 v[28:31], v[224:227], v[156:159], v[28:31]
	v_mfma_f32_16x16x32_bf16 v[20:23], v[216:219], v[196:199], v[20:23]
	v_mfma_f32_16x16x32_bf16 v[12:15], v[224:227], v[196:199], v[12:15]
	v_mfma_f32_16x16x32_bf16 v[8:11], v[216:219], v[208:211], v[8:11]
	v_mfma_f32_16x16x32_bf16 v[4:7], v[224:227], v[208:211], v[4:7]
	v_mfma_f32_16x16x32_bf16 v[52:55], v[220:223], v[152:155], v[52:55]
	v_mfma_f32_16x16x32_bf16 v[44:47], v[228:231], v[152:155], v[44:47]
	v_mfma_f32_16x16x32_bf16 v[36:39], v[220:223], v[160:163], v[36:39]
	v_mfma_f32_16x16x32_bf16 v[28:31], v[228:231], v[160:163], v[28:31]
	v_mfma_f32_16x16x32_bf16 v[20:23], v[220:223], v[200:203], v[20:23]
	v_mfma_f32_16x16x32_bf16 v[12:15], v[228:231], v[200:203], v[12:15]
	s_setprio 2
	s_barrier
	v_mfma_f32_16x16x32_bf16 v[8:11], v[220:223], v[212:215], v[8:11]
	v_mfma_f32_16x16x32_bf16 v[4:7], v[228:231], v[212:215], v[4:7]
	s_setprio 0
	s_add_i32 s56, 0, 0x18000
	s_add_u32 s44, s44, s8
	s_addc_u32 s45, s45, 0
	s_mov_b32 m0, s66
	ds_read_b128 v[148:151], v195 offset:32768
	ds_read_b128 v[152:155], v195 offset:33792
	ds_read_b128 v[156:159], v195 offset:34816
	ds_read_b128 v[160:163], v195 offset:35840
	ds_read_b128 v[196:199], v195 offset:36864
	ds_read_b128 v[200:203], v195 offset:37888
	ds_read_b128 v[208:211], v195 offset:38912
	ds_read_b128 v[212:215], v195 offset:39936
	global_load_lds_dwordx4 v180, s[44:45]
	s_mov_b32 m0, s67
	s_nop 0
	global_load_lds_dwordx4 v182, s[44:45]
	s_waitcnt lgkmcnt(8)
	s_barrier
; #define PG8_STAGE(bufoff, gbase, voff) do { _Pragma("unroll") for (int _i = 0; _i < 2; ++_i) \
;     __builtin_amdgcn_global_load_lds((const unsigned*)((const char*)(gbase) + (voff)[_i]), (LAS unsigned*)(lds + (bufoff) + ldsw + _i * 8192), 16, 0, 0); } while (0)
; #define PG8_LDA(dst, b, h) do { _Pragma("unroll") for (int m = 0; m < 4; ++m) _Pragma("unroll") for (int k = 0; k < 2; ++k) dst[m][k] = *(const LAS bf16x8*)(lds + PG8_SA(b, h) + aoff + m * 2048 + k * 1024); } while (0)
; #define PG8_LDB(dst, b, h) do { _Pragma("unroll") for (int n = 0; n < 2; ++n) _Pragma("unroll") for (int k = 0; k < 2; ++k) dst[n][k] = *(const LAS bf16x8*)(lds + PG8_SB(b, h) + boff + n * 2048 + k * 1024); } while (0)
; #define PG8_MMA(ai, bj, At, Bt) do { __builtin_amdgcn_s_setprio(1); _Pragma("unroll") for (int m = 0; m < 4; ++m) _Pragma("unroll") for (int n = 0; n < 2; ++n) _Pragma("unroll") for (int k = 0; k < 2; ++k) \
;     acc[ai][bj][m][n] = __builtin_amdgcn_mfma_f32_16x16x32_bf16(Bt[n][k], At[m][k], acc[ai][bj][m][n], 0, 0, 0); __builtin_amdgcn_s_setprio(0); } while (0)
; #define PG8_WAIT_V(n) asm volatile("s_waitcnt vmcnt(" #n ")" ::: "memory")
; #define PG8_WAIT_L(n) asm volatile("s_waitcnt lgkmcnt(" #n ")" ::: "memory")
; #define PG8_BAR __builtin_amdgcn_s_barrier()
; #define PG8_SCHED __builtin_amdgcn_sched_barrier(0)
; template <class Epi>
; DI void gemm_phase(LAS unsigned char* lds, const Gemm g, const Epi& E) {
;     ...
;       PG8_WAIT_L(8); PG8_BAR; PG8_WAIT_L(0); PG8_MMA(0, 0, At, B0); PG8_BAR; PG8_SCHED;
;       PG8_LDB(B1, 1, 1); PG8_STAGE(PG8_SB(1, 0), b3, voffB);
;       PG8_BAR; PG8_WAIT_L(0); PG8_MMA(0, 1, At, B1); PG8_BAR;
;       PG8_LDA(At, 1, 1); PG8_STAGE(PG8_SA(1, 0), a3, voffA);
;       PG8_BAR; PG8_WAIT_L(0); PG8_MMA(1, 0, At, B0); PG8_BAR; PG8_SCHED;
;       PG8_STAGE(PG8_SB(1, 1), b3 + hstepB, voffB);
;       PG8_WAIT_V(6); PG8_BAR; PG8_MMA(1, 1, At, B1); PG8_BAR;
	s_setprio 1
	s_waitcnt lgkmcnt(0)
	v_mfma_f32_16x16x32_bf16 v[128:131], v[132:135], v[148:151], v[128:131]
	v_mfma_f32_16x16x32_bf16 v[124:127], v[140:143], v[148:151], v[124:127]
	v_mfma_f32_16x16x32_bf16 v[116:119], v[132:135], v[156:159], v[116:119]
	v_mfma_f32_16x16x32_bf16 v[108:111], v[140:143], v[156:159], v[108:111]
	v_mfma_f32_16x16x32_bf16 v[100:103], v[132:135], v[196:199], v[100:103]
	v_mfma_f32_16x16x32_bf16 v[92:95], v[140:143], v[196:199], v[92:95]
	v_mfma_f32_16x16x32_bf16 v[84:87], v[132:135], v[208:211], v[84:87]
	v_mfma_f32_16x16x32_bf16 v[76:79], v[140:143], v[208:211], v[76:79]
	v_mfma_f32_16x16x32_bf16 v[128:131], v[136:139], v[152:155], v[128:131]
	v_mfma_f32_16x16x32_bf16 v[124:127], v[144:147], v[152:155], v[124:127]
	v_mfma_f32_16x16x32_bf16 v[116:119], v[136:139], v[160:163], v[116:119]
	v_mfma_f32_16x16x32_bf16 v[108:111], v[144:147], v[160:163], v[108:111]
	v_mfma_f32_16x16x32_bf16 v[100:103], v[136:139], v[200:203], v[100:103]
	v_mfma_f32_16x16x32_bf16 v[92:95], v[144:147], v[200:203], v[92:95]
	s_setprio 2
	s_barrier
	v_mfma_f32_16x16x32_bf16 v[84:87], v[136:139], v[212:215], v[84:87]
	v_mfma_f32_16x16x32_bf16 v[76:79], v[144:147], v[212:215], v[76:79]
	s_setprio 0
	s_add_i32 s44, 0, 0x1c000
	s_add_i32 s45, s56, s63
	s_mov_b32 m0, s45
	ds_read_b128 v[216:219], v248 offset:49152
	ds_read_b128 v[220:223], v248 offset:50176
	ds_read_b128 v[224:227], v248 offset:51200
	ds_read_b128 v[228:231], v248 offset:52224
	global_load_lds_dwordx4 v2, s[98:99]
	s_add_i32 m0, s45, 0x2000
	s_nop 0
	global_load_lds_dwordx4 v184, s[98:99]
	s_barrier
	s_setprio 1
	s_waitcnt lgkmcnt(0)
	v_mfma_f32_16x16x32_bf16 v[120:123], v[216:219], v[148:151], v[120:123]
	v_mfma_f32_16x16x32_bf16 v[112:115], v[224:227], v[148:151], v[112:115]
	v_mfma_f32_16x16x32_bf16 v[104:107], v[216:219], v[156:159], v[104:107]
	v_mfma_f32_16x16x32_bf16 v[96:99], v[224:227], v[156:159], v[96:99]
	v_mfma_f32_16x16x32_bf16 v[88:91], v[216:219], v[196:199], v[88:91]
	v_mfma_f32_16x16x32_bf16 v[80:83], v[224:227], v[196:199], v[80:83]
	v_mfma_f32_16x16x32_bf16 v[72:75], v[216:219], v[208:211], v[72:75]
	v_mfma_f32_16x16x32_bf16 v[68:71], v[224:227], v[208:211], v[68:71]
	v_mfma_f32_16x16x32_bf16 v[120:123], v[220:223], v[152:155], v[120:123]
	v_mfma_f32_16x16x32_bf16 v[112:115], v[228:231], v[152:155], v[112:115]
	v_mfma_f32_16x16x32_bf16 v[104:107], v[220:223], v[160:163], v[104:107]
	v_mfma_f32_16x16x32_bf16 v[96:99], v[228:231], v[160:163], v[96:99]
	v_mfma_f32_16x16x32_bf16 v[88:91], v[220:223], v[200:203], v[88:91]
	v_mfma_f32_16x16x32_bf16 v[80:83], v[228:231], v[200:203], v[80:83]
	s_setprio 2
	s_barrier
	v_mfma_f32_16x16x32_bf16 v[72:75], v[220:223], v[212:215], v[72:75]
	v_mfma_f32_16x16x32_bf16 v[68:71], v[228:231], v[212:215], v[68:71]
	s_setprio 0
	s_mov_b32 m0, s69
	ds_read_b128 v[148:151], v195 offset:49152
	ds_read_b128 v[152:155], v195 offset:50176
	ds_read_b128 v[156:159], v195 offset:51200
	ds_read_b128 v[160:163], v195 offset:52224
	ds_read_b128 v[196:199], v195 offset:53248
	ds_read_b128 v[200:203], v195 offset:54272
	ds_read_b128 v[208:211], v195 offset:55296
	ds_read_b128 v[212:215], v195 offset:56320
	global_load_lds_dwordx4 v180, s[100:101]
	s_mov_b32 m0, s71
	s_nop 0
	global_load_lds_dwordx4 v182, s[100:101]
	s_waitcnt vmcnt(10)
	s_barrier
	s_setprio 1
	s_waitcnt lgkmcnt(0)
	v_mfma_f32_16x16x32_bf16 v[64:67], v[132:135], v[148:151], v[64:67]
	v_mfma_f32_16x16x32_bf16 v[60:63], v[140:143], v[148:151], v[60:63]
	v_mfma_f32_16x16x32_bf16 v[56:59], v[132:135], v[156:159], v[56:59]
	v_mfma_f32_16x16x32_bf16 v[48:51], v[140:143], v[156:159], v[48:51]
	v_mfma_f32_16x16x32_bf16 v[40:43], v[132:135], v[196:199], v[40:43]
	v_mfma_f32_16x16x32_bf16 v[32:35], v[140:143], v[196:199], v[32:35]
	v_mfma_f32_16x16x32_bf16 v[24:27], v[132:135], v[208:211], v[24:27]
	v_mfma_f32_16x16x32_bf16 v[16:19], v[140:143], v[208:211], v[16:19]
	v_mfma_f32_16x16x32_bf16 v[64:67], v[136:139], v[152:155], v[64:67]
	v_mfma_f32_16x16x32_bf16 v[60:63], v[144:147], v[152:155], v[60:63]
	v_mfma_f32_16x16x32_bf16 v[56:59], v[136:139], v[160:163], v[56:59]
	v_mfma_f32_16x16x32_bf16 v[48:51], v[144:147], v[160:163], v[48:51]
	v_mfma_f32_16x16x32_bf16 v[40:43], v[136:139], v[200:203], v[40:43]
	v_mfma_f32_16x16x32_bf16 v[32:35], v[144:147], v[200:203], v[32:35]
	s_setprio 2
	s_barrier
	v_mfma_f32_16x16x32_bf16 v[24:27], v[136:139], v[212:215], v[24:27]
	v_mfma_f32_16x16x32_bf16 v[16:19], v[144:147], v[212:215], v[16:19]
	s_setprio 0
	ds_read_b128 v[132:135], v248
	ds_read_b128 v[136:139], v248 offset:1024
	ds_read_b128 v[140:143], v248 offset:2048
	ds_read_b128 v[144:147], v248 offset:3072
	s_add_i32 s44, s44, s63
	v_lshl_add_u64 v[246:247], v[238:239], 0, s[84:85]
	s_mov_b32 m0, s44
	s_nop 0
	global_load_lds_dwordx4 v[246:247], off
	v_lshl_add_u64 v[246:247], v[240:241], 0, s[84:85]
	s_add_i32 m0, s44, 0x2000
	s_nop 0
	global_load_lds_dwordx4 v[246:247], off
	s_waitcnt vmcnt(6)
	s_barrier
	s_setprio 1
	v_mfma_f32_16x16x32_bf16 v[52:55], v[216:219], v[148:151], v[52:55]
	v_mfma_f32_16x16x32_bf16 v[44:47], v[224:227], v[148:151], v[44:47]
	v_mfma_f32_16x16x32_bf16 v[36:39], v[216:219], v[156:159], v[36:39]
	v_mfma_f32_16x16x32_bf16 v[28:31], v[224:227], v[156:159], v[28:31]
	v_mfma_f32_16x16x32_bf16 v[20:23], v[216:219], v[196:199], v[20:23]
	v_mfma_f32_16x16x32_bf16 v[12:15], v[224:227], v[196:199], v[12:15]
	v_mfma_f32_16x16x32_bf16 v[8:11], v[216:219], v[208:211], v[8:11]
	v_mfma_f32_16x16x32_bf16 v[4:7], v[224:227], v[208:211], v[4:7]
	v_mfma_f32_16x16x32_bf16 v[52:55], v[220:223], v[152:155], v[52:55]
	v_mfma_f32_16x16x32_bf16 v[44:47], v[228:231], v[152:155], v[44:47]
	v_mfma_f32_16x16x32_bf16 v[36:39], v[220:223], v[160:163], v[36:39]
	v_mfma_f32_16x16x32_bf16 v[28:31], v[228:231], v[160:163], v[28:31]
	v_mfma_f32_16x16x32_bf16 v[20:23], v[220:223], v[200:203], v[20:23]
	v_mfma_f32_16x16x32_bf16 v[12:15], v[228:231], v[200:203], v[12:15]
	s_setprio 2
	s_barrier
	v_mfma_f32_16x16x32_bf16 v[8:11], v[220:223], v[212:215], v[8:11]
	v_mfma_f32_16x16x32_bf16 v[4:7], v[228:231], v[212:215], v[4:7]
	s_setprio 0
	s_add_u32 s42, s42, 0x100
	s_addc_u32 s43, s43, 0
	s_add_u32 s58, s58, 0x100
	s_addc_u32 s59, s59, 0
	s_cmp_ge_u32 s78, s68
	s_mov_b32 s44, s78
	s_cbranch_scc0 .LBB0_514
